# residual-GEMM epilogues (out-proj, W2, both layers): residual loads hoisted into a register ring with counted vmcnt waits instead of one round trip per 8 outputs
# speedup vs baseline: 1.0058x; 1.0058x over previous
; __device__ __forceinline__ unsigned cvt_pk_bf16(float lo, float hi) { unsigned r; asm volatile("v_cvt_pk_bf16_f32 %0, %1, %2" : "=v"(r) : "v"(lo), "v"(hi)); return r; }
; __device__ __forceinline__ void ld8(const bf16_t* p, f32x4& a, f32x4& b) { const u32x4 r = *(const u32x4*)p;
;     a = (f32x4){__uint_as_float(r.x << 16), __uint_as_float(r.x & 0xffff0000u), __uint_as_float(r.y << 16), __uint_as_float(r.y & 0xffff0000u)};
;     b = (f32x4){__uint_as_float(r.z << 16), __uint_as_float(r.z & 0xffff0000u), __uint_as_float(r.w << 16), __uint_as_float(r.w & 0xffff0000u)}; }
; __device__ __forceinline__ void st8(bf16_t* p, f32x4 a, f32x4 b) { u32x4 w; w.x = cvt_pk_bf16(a[0], a[1]); w.y = cvt_pk_bf16(a[2], a[3]); w.z = cvt_pk_bf16(b[0], b[1]); w.w = cvt_pk_bf16(b[2], b[3]); *(u32x4*)p = w; }
;     __device__ __forceinline__ void operator()(const f32x4 (&acc)[2][2][4][2], const Unit& u, int wr, int wc, int fr, int fq) const {
;     ...
;             for (int n = 0; n < 2; ++n) gv[bj][n] = *(const f32x4*)(gp + col0 + bj * HALF + 4 * n);
; #pragma unroll
;         for (int ai = 0; ai < 2; ++ai)
; #pragma unroll
;             for (int m = 0; m < 4; ++m) { const size_t ro = (size_t)(wr * 64 + fr + ai * HALF + m * 16) * 1024 + col0;
; #pragma unroll
;                 for (int bj = 0; bj < 2; ++bj) {
;                     f32x4 r0, r1; ld8(rb + ro + bj * HALF, r0, r1);
;                     st8(ob + ro + bj * HALF, r0 + gv[bj][0] * acc[ai][bj][m][0], r1 + gv[bj][1] * acc[ai][bj][m][1]); } }
.LBB0_680:
	v_lshl_or_b32 v176, s59, 8, v179
	v_ashrrev_i32_e32 v177, 31, v176
	v_lshl_add_u64 v[192:193], v[152:153], 0, v[176:177]
	v_lshl_add_u64 v[132:133], v[176:177], 2, s[28:29]
	v_lshl_add_u64 v[194:195], v[192:193], 2, s[24:25]
	global_load_dwordx4 v[184:187], v[194:195], off
	global_load_dwordx4 v[140:143], v[132:133], off
	global_load_dwordx4 v[136:139], v[132:133], off offset:16
	global_load_dwordx4 v[188:191], v[194:195], off offset:16
	global_load_dwordx4 v[128:131], v[132:133], off offset:528
	s_nop 0
	global_load_dwordx4 v[132:135], v[132:133], off offset:512
	v_lshl_add_u64 v[192:193], v[192:193], 1, s[22:23]
	s_andn2_b64 vcc, exec, s[0:1]
	s_mov_b64 s[0:1], -1
	global_load_dwordx4 v[198:201], v[194:195], off offset:512
	global_load_dwordx4 v[202:205], v[194:195], off offset:528
	v_lshl_add_u64 v[196:197], v[154:155], 0, v[176:177]
	v_lshl_add_u64 v[196:197], v[196:197], 2, s[24:25]
	global_load_dwordx4 v[206:209], v[196:197], off
	v_lshl_add_u64 v[196:197], v[154:155], 0, v[176:177]
	v_lshl_add_u64 v[196:197], v[196:197], 2, s[24:25]
	global_load_dwordx4 v[210:213], v[196:197], off offset:16
	v_lshl_add_u64 v[196:197], v[154:155], 0, v[176:177]
	v_lshl_add_u64 v[196:197], v[196:197], 2, s[24:25]
	global_load_dwordx4 v[214:217], v[196:197], off offset:512
	v_lshl_add_u64 v[196:197], v[154:155], 0, v[176:177]
	v_lshl_add_u64 v[196:197], v[196:197], 2, s[24:25]
	global_load_dwordx4 v[218:221], v[196:197], off offset:528
	v_lshl_add_u64 v[196:197], v[156:157], 0, v[176:177]
	v_lshl_add_u64 v[196:197], v[196:197], 2, s[24:25]
	global_load_dwordx4 v[222:225], v[196:197], off
	v_lshl_add_u64 v[196:197], v[156:157], 0, v[176:177]
	v_lshl_add_u64 v[196:197], v[196:197], 2, s[24:25]
	global_load_dwordx4 v[226:229], v[196:197], off offset:16
	v_lshl_add_u64 v[196:197], v[156:157], 0, v[176:177]
	v_lshl_add_u64 v[196:197], v[196:197], 2, s[24:25]
	global_load_dwordx4 v[240:243], v[196:197], off offset:512
	v_lshl_add_u64 v[196:197], v[156:157], 0, v[176:177]
	v_lshl_add_u64 v[196:197], v[196:197], 2, s[24:25]
	global_load_dwordx4 v[244:247], v[196:197], off offset:528
	v_lshl_add_u64 v[196:197], v[158:159], 0, v[176:177]
	v_lshl_add_u64 v[196:197], v[196:197], 2, s[24:25]
	global_load_dwordx4 v[248:251], v[196:197], off
	s_waitcnt vmcnt(0)
	v_pk_fma_f32 v[124:125], v[124:125], v[140:141], v[184:185]
	v_pk_fma_f32 v[126:127], v[126:127], v[142:143], v[186:187]
	v_pk_fma_f32 v[184:185], v[122:123], v[138:139], v[190:191]
	v_pk_fma_f32 v[122:123], v[120:121], v[136:137], v[188:189]
	v_cvt_pk_bf16_f32 v120, v124, v125
	v_cvt_pk_bf16_f32 v121, v126, v127
	s_nop 0
	v_cvt_pk_bf16_f32 v122, v122, v123
	v_cvt_pk_bf16_f32 v123, v184, v185
	global_store_dwordx4 v[192:193], v[120:123], off
	s_nop 0
	v_lshl_add_u64 v[184:185], v[154:155], 0, v[176:177]
	v_lshl_add_u64 v[186:187], v[184:185], 2, s[24:25]
	s_nop 0
	v_pk_fma_f32 v[112:113], v[112:113], v[132:133], v[198:199]
	s_nop 0
	v_pk_fma_f32 v[120:121], v[106:107], v[130:131], v[204:205]
	v_pk_fma_f32 v[106:107], v[104:105], v[128:129], v[202:203]
	v_lshl_add_u64 v[196:197], v[158:159], 0, v[176:177]
	v_lshl_add_u64 v[196:197], v[196:197], 2, s[24:25]
	global_load_dwordx4 v[202:205], v[196:197], off offset:512
	v_pk_fma_f32 v[114:115], v[114:115], v[134:135], v[200:201]
	v_lshl_add_u64 v[196:197], v[158:159], 0, v[176:177]
	v_lshl_add_u64 v[196:197], v[196:197], 2, s[24:25]
	global_load_dwordx4 v[198:201], v[196:197], off offset:16
	v_cvt_pk_bf16_f32 v104, v112, v113
	s_nop 0
	v_cvt_pk_bf16_f32 v105, v114, v115
	v_cvt_pk_bf16_f32 v106, v106, v107
	v_cvt_pk_bf16_f32 v107, v120, v121
	global_store_dwordx4 v[192:193], v[104:107], off offset:256
	s_nop 0
	v_lshl_add_u64 v[120:121], v[184:185], 1, s[22:23]
	s_nop 0
	v_pk_fma_f32 v[106:107], v[118:119], v[142:143], v[208:209]
	v_pk_fma_f32 v[104:105], v[116:117], v[140:141], v[206:207]
	v_lshl_add_u64 v[196:197], v[158:159], 0, v[176:177]
	v_lshl_add_u64 v[196:197], v[196:197], 2, s[24:25]
	global_load_dwordx4 v[206:209], v[196:197], off offset:528
	s_nop 0
	v_pk_fma_f32 v[110:111], v[110:111], v[138:139], v[212:213]
	v_pk_fma_f32 v[108:109], v[108:109], v[136:137], v[210:211]
	v_lshl_add_u64 v[196:197], v[160:161], 0, v[176:177]
	v_lshl_add_u64 v[196:197], v[196:197], 2, s[24:25]
	global_load_dwordx4 v[210:213], v[196:197], off
	v_cvt_pk_bf16_f32 v104, v104, v105
	v_cvt_pk_bf16_f32 v105, v106, v107
	v_lshl_add_u64 v[112:113], v[156:157], 0, v[176:177]
	v_cvt_pk_bf16_f32 v106, v108, v109
	v_cvt_pk_bf16_f32 v107, v110, v111
	global_store_dwordx4 v[120:121], v[104:107], off
	s_nop 0
	v_lshl_add_u64 v[114:115], v[112:113], 2, s[24:25]
	s_nop 0
	v_pk_fma_f32 v[96:97], v[96:97], v[132:133], v[214:215]
	s_nop 0
	v_pk_fma_f32 v[104:105], v[90:91], v[130:131], v[220:221]
	v_pk_fma_f32 v[90:91], v[88:89], v[128:129], v[218:219]
	v_lshl_add_u64 v[196:197], v[160:161], 0, v[176:177]
	v_lshl_add_u64 v[196:197], v[196:197], 2, s[24:25]
	global_load_dwordx4 v[218:221], v[196:197], off offset:512
	v_pk_fma_f32 v[98:99], v[98:99], v[134:135], v[216:217]
	v_lshl_add_u64 v[196:197], v[160:161], 0, v[176:177]
	v_lshl_add_u64 v[196:197], v[196:197], 2, s[24:25]
	global_load_dwordx4 v[214:217], v[196:197], off offset:16
	v_cvt_pk_bf16_f32 v88, v96, v97
	s_nop 0
	v_cvt_pk_bf16_f32 v89, v98, v99
	v_cvt_pk_bf16_f32 v90, v90, v91
	v_cvt_pk_bf16_f32 v91, v104, v105
	global_store_dwordx4 v[120:121], v[88:91], off offset:256
	s_nop 0
	v_lshl_add_u64 v[104:105], v[112:113], 1, s[22:23]
	s_nop 0
	v_pk_fma_f32 v[90:91], v[102:103], v[142:143], v[224:225]
	v_pk_fma_f32 v[88:89], v[100:101], v[140:141], v[222:223]
	v_lshl_add_u64 v[196:197], v[160:161], 0, v[176:177]
; __device__ __forceinline__ unsigned cvt_pk_bf16(float lo, float hi) { unsigned r; asm volatile("v_cvt_pk_bf16_f32 %0, %1, %2" : "=v"(r) : "v"(lo), "v"(hi)); return r; }
; __device__ __forceinline__ void ld8(const bf16_t* p, f32x4& a, f32x4& b) { const u32x4 r = *(const u32x4*)p;
;     a = (f32x4){__uint_as_float(r.x << 16), __uint_as_float(r.x & 0xffff0000u), __uint_as_float(r.y << 16), __uint_as_float(r.y & 0xffff0000u)};
;     b = (f32x4){__uint_as_float(r.z << 16), __uint_as_float(r.z & 0xffff0000u), __uint_as_float(r.w << 16), __uint_as_float(r.w & 0xffff0000u)}; }
; __device__ __forceinline__ void st8(bf16_t* p, f32x4 a, f32x4 b) { u32x4 w; w.x = cvt_pk_bf16(a[0], a[1]); w.y = cvt_pk_bf16(a[2], a[3]); w.z = cvt_pk_bf16(b[0], b[1]); w.w = cvt_pk_bf16(b[2], b[3]); *(u32x4*)p = w; }
;     __device__ __forceinline__ void operator()(const f32x4 (&acc)[2][2][4][2], const Unit& u, int wr, int wc, int fr, int fq) const {
;     ...
;             for (int n = 0; n < 2; ++n) gv[bj][n] = *(const f32x4*)(gp + col0 + bj * HALF + 4 * n);
; #pragma unroll
;         for (int ai = 0; ai < 2; ++ai)
; #pragma unroll
;             for (int m = 0; m < 4; ++m) { const size_t ro = (size_t)(wr * 64 + fr + ai * HALF + m * 16) * 1024 + col0;
; #pragma unroll
;                 for (int bj = 0; bj < 2; ++bj) {
;                     f32x4 r0, r1; ld8(rb + ro + bj * HALF, r0, r1);
;                     st8(ob + ro + bj * HALF, r0 + gv[bj][0] * acc[ai][bj][m][0], r1 + gv[bj][1] * acc[ai][bj][m][1]); } }
	v_lshl_add_u64 v[196:197], v[196:197], 2, s[24:25]
	global_load_dwordx4 v[222:225], v[196:197], off offset:528
	s_nop 0
	v_pk_fma_f32 v[94:95], v[94:95], v[138:139], v[228:229]
	v_pk_fma_f32 v[92:93], v[92:93], v[136:137], v[226:227]
	v_lshl_add_u64 v[196:197], v[162:163], 0, v[176:177]
	v_lshl_add_u64 v[196:197], v[196:197], 2, s[24:25]
	global_load_dwordx4 v[226:229], v[196:197], off
	v_cvt_pk_bf16_f32 v88, v88, v89
	v_cvt_pk_bf16_f32 v89, v90, v91
	v_lshl_add_u64 v[96:97], v[158:159], 0, v[176:177]
	v_cvt_pk_bf16_f32 v90, v92, v93
	v_cvt_pk_bf16_f32 v91, v94, v95
	global_store_dwordx4 v[104:105], v[88:91], off
	s_nop 0
	v_lshl_add_u64 v[98:99], v[96:97], 2, s[24:25]
	s_nop 0
	v_pk_fma_f32 v[80:81], v[80:81], v[132:133], v[240:241]
	s_nop 0
	v_pk_fma_f32 v[88:89], v[74:75], v[130:131], v[246:247]
	v_pk_fma_f32 v[74:75], v[72:73], v[128:129], v[244:245]
	v_lshl_add_u64 v[196:197], v[162:163], 0, v[176:177]
	v_lshl_add_u64 v[196:197], v[196:197], 2, s[24:25]
	global_load_dwordx4 v[244:247], v[196:197], off offset:512
	v_pk_fma_f32 v[82:83], v[82:83], v[134:135], v[242:243]
	v_lshl_add_u64 v[196:197], v[162:163], 0, v[176:177]
	v_lshl_add_u64 v[196:197], v[196:197], 2, s[24:25]
	global_load_dwordx4 v[240:243], v[196:197], off offset:16
	v_cvt_pk_bf16_f32 v72, v80, v81
	s_nop 0
	v_cvt_pk_bf16_f32 v73, v82, v83
	v_cvt_pk_bf16_f32 v74, v74, v75
	v_cvt_pk_bf16_f32 v75, v88, v89
	global_store_dwordx4 v[104:105], v[72:75], off offset:256
	s_nop 0
	v_lshl_add_u64 v[88:89], v[96:97], 1, s[22:23]
	s_nop 0
	v_pk_fma_f32 v[74:75], v[86:87], v[142:143], v[250:251]
	v_pk_fma_f32 v[72:73], v[84:85], v[140:141], v[248:249]
	v_lshl_add_u64 v[196:197], v[162:163], 0, v[176:177]
	v_lshl_add_u64 v[196:197], v[196:197], 2, s[24:25]
	global_load_dwordx4 v[248:251], v[196:197], off offset:528
	s_nop 0
	s_waitcnt vmcnt(14)
	v_pk_fma_f32 v[78:79], v[78:79], v[138:139], v[200:201]
	v_pk_fma_f32 v[76:77], v[76:77], v[136:137], v[198:199]
	v_lshl_add_u64 v[196:197], v[164:165], 0, v[176:177]
	v_lshl_add_u64 v[196:197], v[196:197], 2, s[24:25]
	global_load_dwordx4 v[198:201], v[196:197], off
	v_cvt_pk_bf16_f32 v72, v72, v73
	v_cvt_pk_bf16_f32 v73, v74, v75
	v_lshl_add_u64 v[80:81], v[160:161], 0, v[176:177]
	v_cvt_pk_bf16_f32 v74, v76, v77
	v_cvt_pk_bf16_f32 v75, v78, v79
	global_store_dwordx4 v[88:89], v[72:75], off
	s_nop 0
	v_lshl_add_u64 v[82:83], v[80:81], 2, s[24:25]
	s_nop 0
	v_pk_fma_f32 v[68:69], v[68:69], v[132:133], v[202:203]
	s_nop 0
	s_waitcnt vmcnt(14)
	v_pk_fma_f32 v[72:73], v[66:67], v[130:131], v[208:209]
	v_pk_fma_f32 v[66:67], v[64:65], v[128:129], v[206:207]
	v_lshl_add_u64 v[196:197], v[164:165], 0, v[176:177]
	v_lshl_add_u64 v[196:197], v[196:197], 2, s[24:25]
	global_load_dwordx4 v[206:209], v[196:197], off offset:512
	v_pk_fma_f32 v[70:71], v[70:71], v[134:135], v[204:205]
	v_lshl_add_u64 v[196:197], v[164:165], 0, v[176:177]
	v_lshl_add_u64 v[196:197], v[196:197], 2, s[24:25]
	global_load_dwordx4 v[202:205], v[196:197], off offset:16
	v_cvt_pk_bf16_f32 v64, v68, v69
	s_nop 0
	v_cvt_pk_bf16_f32 v65, v70, v71
	v_cvt_pk_bf16_f32 v66, v66, v67
	v_cvt_pk_bf16_f32 v67, v72, v73
	global_store_dwordx4 v[88:89], v[64:67], off offset:256
	s_nop 0
	v_lshl_add_u64 v[72:73], v[80:81], 1, s[22:23]
	s_nop 0
	s_waitcnt vmcnt(16)
	v_pk_fma_f32 v[60:61], v[60:61], v[140:141], v[210:211]
	s_nop 0
	s_waitcnt vmcnt(13)
	v_pk_fma_f32 v[64:65], v[58:59], v[138:139], v[216:217]
	v_pk_fma_f32 v[58:59], v[56:57], v[136:137], v[214:215]
	v_lshl_add_u64 v[196:197], v[166:167], 0, v[176:177]
	v_lshl_add_u64 v[196:197], v[196:197], 2, s[24:25]
	global_load_dwordx4 v[214:217], v[196:197], off
	v_pk_fma_f32 v[62:63], v[62:63], v[142:143], v[212:213]
	v_lshl_add_u64 v[196:197], v[164:165], 0, v[176:177]
	v_lshl_add_u64 v[196:197], v[196:197], 2, s[24:25]
	global_load_dwordx4 v[210:213], v[196:197], off offset:528
	v_cvt_pk_bf16_f32 v56, v60, v61
	s_nop 0
	v_cvt_pk_bf16_f32 v57, v62, v63
	v_cvt_pk_bf16_f32 v58, v58, v59
	v_cvt_pk_bf16_f32 v59, v64, v65
	global_store_dwordx4 v[72:73], v[56:59], off
	s_nop 0
	v_lshl_add_u64 v[64:65], v[162:163], 0, v[176:177]
	v_lshl_add_u64 v[66:67], v[64:65], 2, s[24:25]
	s_nop 0
	v_pk_fma_f32 v[48:49], v[48:49], v[132:133], v[218:219]
	s_nop 0
	s_waitcnt vmcnt(14)
; __device__ __forceinline__ unsigned cvt_pk_bf16(float lo, float hi) { unsigned r; asm volatile("v_cvt_pk_bf16_f32 %0, %1, %2" : "=v"(r) : "v"(lo), "v"(hi)); return r; }
; __device__ __forceinline__ void ld8(const bf16_t* p, f32x4& a, f32x4& b) { const u32x4 r = *(const u32x4*)p;
;     a = (f32x4){__uint_as_float(r.x << 16), __uint_as_float(r.x & 0xffff0000u), __uint_as_float(r.y << 16), __uint_as_float(r.y & 0xffff0000u)};
;     b = (f32x4){__uint_as_float(r.z << 16), __uint_as_float(r.z & 0xffff0000u), __uint_as_float(r.w << 16), __uint_as_float(r.w & 0xffff0000u)}; }
; __device__ __forceinline__ void st8(bf16_t* p, f32x4 a, f32x4 b) { u32x4 w; w.x = cvt_pk_bf16(a[0], a[1]); w.y = cvt_pk_bf16(a[2], a[3]); w.z = cvt_pk_bf16(b[0], b[1]); w.w = cvt_pk_bf16(b[2], b[3]); *(u32x4*)p = w; }
;     __device__ __forceinline__ void operator()(const f32x4 (&acc)[2][2][4][2], const Unit& u, int wr, int wc, int fr, int fq) const {
;     ...
;             for (int m = 0; m < 4; ++m) { const size_t ro = (size_t)(wr * 64 + fr + ai * HALF + m * 16) * 1024 + col0;
; #pragma unroll
;                 for (int bj = 0; bj < 2; ++bj) {
;                     f32x4 r0, r1; ld8(rb + ro + bj * HALF, r0, r1);
;                     st8(ob + ro + bj * HALF, r0 + gv[bj][0] * acc[ai][bj][m][0], r1 + gv[bj][1] * acc[ai][bj][m][1]); } }
	v_pk_fma_f32 v[56:57], v[42:43], v[130:131], v[224:225]
	v_pk_fma_f32 v[42:43], v[40:41], v[128:129], v[222:223]
	v_lshl_add_u64 v[196:197], v[166:167], 0, v[176:177]
	v_lshl_add_u64 v[196:197], v[196:197], 2, s[24:25]
	global_load_dwordx4 v[222:225], v[196:197], off offset:512
	v_pk_fma_f32 v[50:51], v[50:51], v[134:135], v[220:221]
	v_lshl_add_u64 v[196:197], v[166:167], 0, v[176:177]
	v_lshl_add_u64 v[196:197], v[196:197], 2, s[24:25]
	global_load_dwordx4 v[218:221], v[196:197], off offset:16
	v_cvt_pk_bf16_f32 v40, v48, v49
	s_nop 0
	v_cvt_pk_bf16_f32 v41, v50, v51
	v_cvt_pk_bf16_f32 v42, v42, v43
	v_cvt_pk_bf16_f32 v43, v56, v57
	global_store_dwordx4 v[72:73], v[40:43], off offset:256
	s_nop 0
	v_lshl_add_u64 v[56:57], v[64:65], 1, s[22:23]
	s_nop 0
	s_waitcnt vmcnt(16)
	v_pk_fma_f32 v[42:43], v[54:55], v[142:143], v[228:229]
	v_pk_fma_f32 v[40:41], v[52:53], v[140:141], v[226:227]
	v_lshl_add_u64 v[196:197], v[166:167], 0, v[176:177]
	v_lshl_add_u64 v[196:197], v[196:197], 2, s[24:25]
	global_load_dwordx4 v[226:229], v[196:197], off offset:528
	s_nop 0
	s_waitcnt vmcnt(14)
	v_pk_fma_f32 v[46:47], v[46:47], v[138:139], v[242:243]
	v_pk_fma_f32 v[44:45], v[44:45], v[136:137], v[240:241]
	v_cvt_pk_bf16_f32 v40, v40, v41
	v_cvt_pk_bf16_f32 v41, v42, v43
	v_lshl_add_u64 v[48:49], v[164:165], 0, v[176:177]
	v_cvt_pk_bf16_f32 v42, v44, v45
	v_cvt_pk_bf16_f32 v43, v46, v47
	global_store_dwordx4 v[56:57], v[40:43], off
	s_nop 0
	v_lshl_add_u64 v[50:51], v[48:49], 2, s[24:25]
	s_nop 0
	v_pk_fma_f32 v[32:33], v[32:33], v[132:133], v[244:245]
	s_nop 0
	s_waitcnt vmcnt(13)
	v_pk_fma_f32 v[40:41], v[26:27], v[130:131], v[250:251]
	v_pk_fma_f32 v[26:27], v[24:25], v[128:129], v[248:249]
	v_pk_fma_f32 v[34:35], v[34:35], v[134:135], v[246:247]
	v_cvt_pk_bf16_f32 v24, v32, v33
	s_nop 0
	v_cvt_pk_bf16_f32 v25, v34, v35
	v_cvt_pk_bf16_f32 v26, v26, v27
	v_cvt_pk_bf16_f32 v27, v40, v41
	global_store_dwordx4 v[56:57], v[24:27], off offset:256
	s_nop 0
	v_lshl_add_u64 v[40:41], v[48:49], 1, s[22:23]
	s_nop 0
	s_waitcnt vmcnt(13)
	v_pk_fma_f32 v[26:27], v[38:39], v[142:143], v[200:201]
	v_pk_fma_f32 v[24:25], v[36:37], v[140:141], v[198:199]
	s_nop 0
	s_waitcnt vmcnt(10)
	v_pk_fma_f32 v[30:31], v[30:31], v[138:139], v[204:205]
	v_pk_fma_f32 v[28:29], v[28:29], v[136:137], v[202:203]
	v_cvt_pk_bf16_f32 v24, v24, v25
	v_cvt_pk_bf16_f32 v25, v26, v27
	v_lshl_add_u64 v[32:33], v[166:167], 0, v[176:177]
	v_cvt_pk_bf16_f32 v26, v28, v29
	v_cvt_pk_bf16_f32 v27, v30, v31
	global_store_dwordx4 v[40:41], v[24:27], off
	s_nop 0
	v_lshl_add_u64 v[34:35], v[32:33], 2, s[24:25]
	s_nop 0
	v_pk_fma_f32 v[16:17], v[16:17], v[132:133], v[206:207]
	s_nop 0
	s_waitcnt vmcnt(8)
	v_pk_fma_f32 v[24:25], v[10:11], v[130:131], v[212:213]
	v_pk_fma_f32 v[10:11], v[8:9], v[128:129], v[210:211]
	v_pk_fma_f32 v[18:19], v[18:19], v[134:135], v[208:209]
	v_cvt_pk_bf16_f32 v8, v16, v17
	s_nop 0
	v_cvt_pk_bf16_f32 v9, v18, v19
	v_cvt_pk_bf16_f32 v10, v10, v11
	v_cvt_pk_bf16_f32 v11, v24, v25
	global_store_dwordx4 v[40:41], v[8:11], off offset:256
	s_nop 0
	v_lshl_add_u64 v[24:25], v[32:33], 1, s[22:23]
	s_nop 0
	v_pk_fma_f32 v[10:11], v[22:23], v[142:143], v[216:217]
	v_pk_fma_f32 v[8:9], v[20:21], v[140:141], v[214:215]
	s_nop 0
	s_waitcnt vmcnt(6)
	v_pk_fma_f32 v[14:15], v[14:15], v[138:139], v[220:221]
	v_pk_fma_f32 v[12:13], v[12:13], v[136:137], v[218:219]
	v_cvt_pk_bf16_f32 v8, v8, v9
	v_cvt_pk_bf16_f32 v9, v10, v11
	s_nop 0
	v_cvt_pk_bf16_f32 v10, v12, v13
	v_cvt_pk_bf16_f32 v11, v14, v15
	global_store_dwordx4 v[24:25], v[8:11], off
	s_nop 0
	s_nop 0
	v_pk_fma_f32 v[4:5], v[4:5], v[132:133], v[222:223]
	s_nop 0
	s_waitcnt vmcnt(5)
	v_pk_fma_f32 v[8:9], v[2:3], v[130:131], v[228:229]
	v_pk_fma_f32 v[2:3], v[0:1], v[128:129], v[226:227]
	v_pk_fma_f32 v[6:7], v[6:7], v[134:135], v[224:225]
	v_cvt_pk_bf16_f32 v0, v4, v5
	s_nop 0
	v_cvt_pk_bf16_f32 v1, v6, v7
	v_cvt_pk_bf16_f32 v2, v2, v3
	v_cvt_pk_bf16_f32 v3, v8, v9
	global_store_dwordx4 v[24:25], v[0:3], off offset:256
	s_cbranch_vccnz .LBB0_666
	s_andn2_b64 vcc, exec, s[10:11]
	s_cbranch_vccnz .LBB0_665
	s_barrier
	s_branch .LBB0_665

; __device__ __forceinline__ unsigned cvt_pk_bf16(float lo, float hi) { unsigned r; asm volatile("v_cvt_pk_bf16_f32 %0, %1, %2" : "=v"(r) : "v"(lo), "v"(hi)); return r; }
; __device__ __forceinline__ void ld8(const bf16_t* p, f32x4& a, f32x4& b) { const u32x4 r = *(const u32x4*)p;
;     a = (f32x4){__uint_as_float(r.x << 16), __uint_as_float(r.x & 0xffff0000u), __uint_as_float(r.y << 16), __uint_as_float(r.y & 0xffff0000u)};
;     b = (f32x4){__uint_as_float(r.z << 16), __uint_as_float(r.z & 0xffff0000u), __uint_as_float(r.w << 16), __uint_as_float(r.w & 0xffff0000u)}; }
; __device__ __forceinline__ void st8(bf16_t* p, f32x4 a, f32x4 b) { u32x4 w; w.x = cvt_pk_bf16(a[0], a[1]); w.y = cvt_pk_bf16(a[2], a[3]); w.z = cvt_pk_bf16(b[0], b[1]); w.w = cvt_pk_bf16(b[2], b[3]); *(u32x4*)p = w; }
;     __device__ __forceinline__ void operator()(const f32x4 (&acc)[2][2][4][2], const Unit& u, int wr, int wc, int fr, int fq) const {
;         const int b = u.pm / 65, w = u.pm % 65;
;         const RT* rb; OT* ob; const float* gp;
;         if (w == 0) { rb = res_ctx + (size_t)b * 256 * 1024; ob = out_ctx + (size_t)b * 256 * 1024; gp = gate + 2 * 6144; }
;         else { const size_t o = ((size_t)b * 16384 + (size_t)(w - 1) * 256) * 1024; rb = res_lat + o; ob = out_lat + o; gp = gate + b * 6144; }
;         const int col0 = u.pn * BM + wc * 32 + 8 * fq;
;         f32x4 gv[2][2];
; #pragma unroll
;         for (int bj = 0; bj < 2; ++bj)
; #pragma unroll
;             for (int n = 0; n < 2; ++n) gv[bj][n] = *(const f32x4*)(gp + col0 + bj * HALF + 4 * n);
; #pragma unroll
;         for (int ai = 0; ai < 2; ++ai)
; #pragma unroll
;             for (int m = 0; m < 4; ++m) { const size_t ro = (size_t)(wr * 64 + fr + ai * HALF + m * 16) * 1024 + col0;
; #pragma unroll
;                 for (int bj = 0; bj < 2; ++bj) {
;                     f32x4 r0, r1; ld8(rb + ro + bj * HALF, r0, r1);
;                     st8(ob + ro + bj * HALF, r0 + gv[bj][0] * acc[ai][bj][m][0], r1 + gv[bj][1] * acc[ai][bj][m][1]); } }
.LBB0_995:
	v_lshl_or_b32 v120, s53, 8, v179
	v_ashrrev_i32_e32 v121, 31, v120
	v_lshl_add_u64 v[122:123], s[18:19], 0, v[152:153]
	v_lshlrev_b64 v[176:177], 1, v[120:121]
	v_lshl_add_u64 v[188:189], v[122:123], 0, v[176:177]
	global_load_dwordx4 v[184:187], v[188:189], off
	v_lshl_add_u64 v[124:125], v[120:121], 2, s[22:23]
	global_load_dwordx4 v[140:143], v[124:125], off
	global_load_dwordx4 v[136:139], v[124:125], off offset:16
	global_load_dwordx4 v[120:123], v[124:125], off offset:528
	s_nop 0
	global_load_dwordx4 v[124:127], v[124:125], off offset:512
	s_and_b64 vcc, exec, s[0:1]
	s_mov_b64 s[0:1], -1
	global_load_dwordx4 v[196:199], v[188:189], off offset:256
	v_lshl_add_u64 v[194:195], s[18:19], 0, v[162:163]
	v_lshl_add_u64 v[194:195], v[194:195], 0, v[176:177]
	global_load_dwordx4 v[200:203], v[194:195], off
	v_lshl_add_u64 v[194:195], s[18:19], 0, v[162:163]
	v_lshl_add_u64 v[194:195], v[194:195], 0, v[176:177]
	global_load_dwordx4 v[204:207], v[194:195], off offset:256
	v_lshl_add_u64 v[194:195], s[18:19], 0, v[164:165]
	v_lshl_add_u64 v[194:195], v[194:195], 0, v[176:177]
	global_load_dwordx4 v[208:211], v[194:195], off
	v_lshl_add_u64 v[194:195], s[18:19], 0, v[164:165]
	v_lshl_add_u64 v[194:195], v[194:195], 0, v[176:177]
	global_load_dwordx4 v[212:215], v[194:195], off offset:256
	v_lshl_add_u64 v[194:195], s[18:19], 0, v[166:167]
	v_lshl_add_u64 v[194:195], v[194:195], 0, v[176:177]
	global_load_dwordx4 v[216:219], v[194:195], off
	v_lshl_add_u64 v[194:195], s[18:19], 0, v[166:167]
	v_lshl_add_u64 v[194:195], v[194:195], 0, v[176:177]
	global_load_dwordx4 v[220:223], v[194:195], off offset:256
	v_lshl_add_u64 v[194:195], s[18:19], 0, v[154:155]
	v_lshl_add_u64 v[194:195], v[194:195], 0, v[176:177]
	global_load_dwordx4 v[224:227], v[194:195], off
	v_lshl_add_u64 v[194:195], s[18:19], 0, v[154:155]
	v_lshl_add_u64 v[194:195], v[194:195], 0, v[176:177]
	global_load_dwordx4 v[228:231], v[194:195], off offset:256
	v_lshl_add_u64 v[194:195], s[18:19], 0, v[156:157]
	v_lshl_add_u64 v[194:195], v[194:195], 0, v[176:177]
	global_load_dwordx4 v[240:243], v[194:195], off
	v_lshl_add_u64 v[194:195], s[18:19], 0, v[156:157]
	v_lshl_add_u64 v[194:195], v[194:195], 0, v[176:177]
	global_load_dwordx4 v[244:247], v[194:195], off offset:256
	v_lshl_add_u64 v[194:195], s[18:19], 0, v[158:159]
	v_lshl_add_u64 v[194:195], v[194:195], 0, v[176:177]
	global_load_dwordx4 v[248:251], v[194:195], off
	s_waitcnt vmcnt(0)
	v_lshlrev_b32_e32 v190, 16, v184
	v_and_b32_e32 v191, 0xffff0000, v184
	v_lshlrev_b32_e32 v184, 16, v185
	v_and_b32_e32 v185, 0xffff0000, v185
	v_lshlrev_b32_e32 v192, 16, v186
	v_and_b32_e32 v193, 0xffff0000, v186
	v_lshlrev_b32_e32 v186, 16, v187
	v_and_b32_e32 v187, 0xffff0000, v187
	v_pk_fma_f32 v[134:135], v[134:135], v[142:143], v[184:185]
	v_pk_fma_f32 v[132:133], v[132:133], v[140:141], v[190:191]
	v_pk_fma_f32 v[184:185], v[130:131], v[138:139], v[186:187]
	v_pk_fma_f32 v[130:131], v[128:129], v[136:137], v[192:193]
	v_cvt_pk_bf16_f32 v128, v132, v133
	v_cvt_pk_bf16_f32 v129, v134, v135
	s_nop 0
	v_cvt_pk_bf16_f32 v130, v130, v131
	v_cvt_pk_bf16_f32 v131, v184, v185
	v_lshl_add_u64 v[184:185], s[18:19], 0, v[162:163]
	global_store_dwordx4 v[188:189], v[128:131], off
	v_lshl_add_u64 v[184:185], v[184:185], 0, v[176:177]
	s_nop 0
	v_lshlrev_b32_e32 v128, 16, v196
	v_and_b32_e32 v129, 0xffff0000, v196
	v_lshlrev_b32_e32 v130, 16, v197
	v_and_b32_e32 v131, 0xffff0000, v197
	v_lshlrev_b32_e32 v132, 16, v198
	v_and_b32_e32 v133, 0xffff0000, v198
	v_lshlrev_b32_e32 v134, 16, v199
	v_and_b32_e32 v135, 0xffff0000, v199
	v_lshl_add_u64 v[194:195], s[18:19], 0, v[158:159]
	v_lshl_add_u64 v[194:195], v[194:195], 0, v[176:177]
	global_load_dwordx4 v[196:199], v[194:195], off offset:256
	v_pk_fma_f32 v[114:115], v[114:115], v[126:127], v[130:131]
	v_pk_fma_f32 v[112:113], v[112:113], v[124:125], v[128:129]
	v_pk_fma_f32 v[128:129], v[110:111], v[122:123], v[134:135]
	v_pk_fma_f32 v[110:111], v[108:109], v[120:121], v[132:133]
	v_cvt_pk_bf16_f32 v108, v112, v113
	v_cvt_pk_bf16_f32 v109, v114, v115
	s_nop 0
	v_cvt_pk_bf16_f32 v110, v110, v111
	v_cvt_pk_bf16_f32 v111, v128, v129
	s_nop 0
	global_store_dwordx4 v[188:189], v[108:111], off offset:256
	s_nop 0
	s_nop 0
	v_lshlrev_b32_e32 v108, 16, v200
	v_and_b32_e32 v109, 0xffff0000, v200
	v_lshlrev_b32_e32 v110, 16, v201
	v_and_b32_e32 v111, 0xffff0000, v201
	v_lshlrev_b32_e32 v112, 16, v202
	v_and_b32_e32 v113, 0xffff0000, v202
	v_lshlrev_b32_e32 v114, 16, v203
	v_and_b32_e32 v115, 0xffff0000, v203
	v_lshl_add_u64 v[194:195], s[18:19], 0, v[160:161]
	v_lshl_add_u64 v[194:195], v[194:195], 0, v[176:177]
	global_load_dwordx4 v[200:203], v[194:195], off
	v_pk_fma_f32 v[110:111], v[118:119], v[142:143], v[110:111]
	v_pk_fma_f32 v[108:109], v[116:117], v[140:141], v[108:109]
	v_pk_fma_f32 v[114:115], v[106:107], v[138:139], v[114:115]
	v_pk_fma_f32 v[106:107], v[104:105], v[136:137], v[112:113]
	v_cvt_pk_bf16_f32 v104, v108, v109
	v_cvt_pk_bf16_f32 v105, v110, v111
	v_lshl_add_u64 v[112:113], s[18:19], 0, v[164:165]
	v_cvt_pk_bf16_f32 v106, v106, v107
	v_cvt_pk_bf16_f32 v107, v114, v115
	v_lshl_add_u64 v[112:113], v[112:113], 0, v[176:177]
	global_store_dwordx4 v[184:185], v[104:107], off
	s_nop 0
	s_nop 0
	v_lshlrev_b32_e32 v104, 16, v204
	v_and_b32_e32 v105, 0xffff0000, v204
	v_lshlrev_b32_e32 v106, 16, v205
	v_and_b32_e32 v107, 0xffff0000, v205
	v_lshlrev_b32_e32 v108, 16, v206
	v_and_b32_e32 v109, 0xffff0000, v206
	v_lshlrev_b32_e32 v110, 16, v207
	v_and_b32_e32 v111, 0xffff0000, v207
	v_lshl_add_u64 v[194:195], s[18:19], 0, v[160:161]
	v_lshl_add_u64 v[194:195], v[194:195], 0, v[176:177]
; __device__ __forceinline__ unsigned cvt_pk_bf16(float lo, float hi) { unsigned r; asm volatile("v_cvt_pk_bf16_f32 %0, %1, %2" : "=v"(r) : "v"(lo), "v"(hi)); return r; }
; __device__ __forceinline__ void ld8(const bf16_t* p, f32x4& a, f32x4& b) { const u32x4 r = *(const u32x4*)p;
;     a = (f32x4){__uint_as_float(r.x << 16), __uint_as_float(r.x & 0xffff0000u), __uint_as_float(r.y << 16), __uint_as_float(r.y & 0xffff0000u)};
;     b = (f32x4){__uint_as_float(r.z << 16), __uint_as_float(r.z & 0xffff0000u), __uint_as_float(r.w << 16), __uint_as_float(r.w & 0xffff0000u)}; }
; __device__ __forceinline__ void st8(bf16_t* p, f32x4 a, f32x4 b) { u32x4 w; w.x = cvt_pk_bf16(a[0], a[1]); w.y = cvt_pk_bf16(a[2], a[3]); w.z = cvt_pk_bf16(b[0], b[1]); w.w = cvt_pk_bf16(b[2], b[3]); *(u32x4*)p = w; }
;     __device__ __forceinline__ void operator()(const f32x4 (&acc)[2][2][4][2], const Unit& u, int wr, int wc, int fr, int fq) const {
;     ...
;             for (int n = 0; n < 2; ++n) gv[bj][n] = *(const f32x4*)(gp + col0 + bj * HALF + 4 * n);
; #pragma unroll
;         for (int ai = 0; ai < 2; ++ai)
; #pragma unroll
;             for (int m = 0; m < 4; ++m) { const size_t ro = (size_t)(wr * 64 + fr + ai * HALF + m * 16) * 1024 + col0;
; #pragma unroll
;                 for (int bj = 0; bj < 2; ++bj) {
;                     f32x4 r0, r1; ld8(rb + ro + bj * HALF, r0, r1);
;                     st8(ob + ro + bj * HALF, r0 + gv[bj][0] * acc[ai][bj][m][0], r1 + gv[bj][1] * acc[ai][bj][m][1]); } }
	global_load_dwordx4 v[204:207], v[194:195], off offset:256
	v_pk_fma_f32 v[98:99], v[98:99], v[126:127], v[106:107]
	v_pk_fma_f32 v[96:97], v[96:97], v[124:125], v[104:105]
	v_pk_fma_f32 v[104:105], v[94:95], v[122:123], v[110:111]
	v_pk_fma_f32 v[94:95], v[92:93], v[120:121], v[108:109]
	v_cvt_pk_bf16_f32 v92, v96, v97
	v_cvt_pk_bf16_f32 v93, v98, v99
	s_nop 0
	v_cvt_pk_bf16_f32 v94, v94, v95
	v_cvt_pk_bf16_f32 v95, v104, v105
	s_nop 0
	global_store_dwordx4 v[184:185], v[92:95], off offset:256
	s_nop 0
	s_nop 0
	v_lshlrev_b32_e32 v92, 16, v208
	v_and_b32_e32 v93, 0xffff0000, v208
	v_lshlrev_b32_e32 v94, 16, v209
	v_and_b32_e32 v95, 0xffff0000, v209
	v_lshlrev_b32_e32 v96, 16, v210
	v_and_b32_e32 v97, 0xffff0000, v210
	v_lshlrev_b32_e32 v98, 16, v211
	v_and_b32_e32 v99, 0xffff0000, v211
	v_pk_fma_f32 v[94:95], v[102:103], v[142:143], v[94:95]
	v_pk_fma_f32 v[92:93], v[100:101], v[140:141], v[92:93]
	v_pk_fma_f32 v[98:99], v[90:91], v[138:139], v[98:99]
	v_pk_fma_f32 v[90:91], v[88:89], v[136:137], v[96:97]
	v_cvt_pk_bf16_f32 v88, v92, v93
	v_cvt_pk_bf16_f32 v89, v94, v95
	v_lshl_add_u64 v[96:97], s[18:19], 0, v[166:167]
	v_cvt_pk_bf16_f32 v90, v90, v91
	v_cvt_pk_bf16_f32 v91, v98, v99
	v_lshl_add_u64 v[96:97], v[96:97], 0, v[176:177]
	global_store_dwordx4 v[112:113], v[88:91], off
	s_nop 0
	s_nop 0
	v_lshlrev_b32_e32 v88, 16, v212
	v_and_b32_e32 v89, 0xffff0000, v212
	v_lshlrev_b32_e32 v90, 16, v213
	v_and_b32_e32 v91, 0xffff0000, v213
	v_lshlrev_b32_e32 v92, 16, v214
	v_and_b32_e32 v93, 0xffff0000, v214
	v_lshlrev_b32_e32 v94, 16, v215
	v_and_b32_e32 v95, 0xffff0000, v215
	v_pk_fma_f32 v[82:83], v[82:83], v[126:127], v[90:91]
	v_pk_fma_f32 v[80:81], v[80:81], v[124:125], v[88:89]
	v_pk_fma_f32 v[88:89], v[78:79], v[122:123], v[94:95]
	v_pk_fma_f32 v[78:79], v[76:77], v[120:121], v[92:93]
	v_cvt_pk_bf16_f32 v76, v80, v81
	v_cvt_pk_bf16_f32 v77, v82, v83
	s_nop 0
	v_cvt_pk_bf16_f32 v78, v78, v79
	v_cvt_pk_bf16_f32 v79, v88, v89
	s_nop 0
	global_store_dwordx4 v[112:113], v[76:79], off offset:256
	s_nop 0
	s_nop 0
	v_lshlrev_b32_e32 v76, 16, v216
	v_and_b32_e32 v77, 0xffff0000, v216
	v_lshlrev_b32_e32 v78, 16, v217
	v_and_b32_e32 v79, 0xffff0000, v217
	v_lshlrev_b32_e32 v80, 16, v218
	v_and_b32_e32 v81, 0xffff0000, v218
	v_lshlrev_b32_e32 v82, 16, v219
	v_and_b32_e32 v83, 0xffff0000, v219
	v_pk_fma_f32 v[78:79], v[86:87], v[142:143], v[78:79]
	v_pk_fma_f32 v[76:77], v[84:85], v[140:141], v[76:77]
	v_pk_fma_f32 v[82:83], v[74:75], v[138:139], v[82:83]
	v_pk_fma_f32 v[74:75], v[72:73], v[136:137], v[80:81]
	v_cvt_pk_bf16_f32 v72, v76, v77
	v_cvt_pk_bf16_f32 v73, v78, v79
	v_lshl_add_u64 v[80:81], s[18:19], 0, v[154:155]
	v_cvt_pk_bf16_f32 v74, v74, v75
	v_cvt_pk_bf16_f32 v75, v82, v83
	v_lshl_add_u64 v[80:81], v[80:81], 0, v[176:177]
	global_store_dwordx4 v[96:97], v[72:75], off
	s_nop 0
	s_nop 0
	v_lshlrev_b32_e32 v72, 16, v220
	v_and_b32_e32 v73, 0xffff0000, v220
	v_lshlrev_b32_e32 v74, 16, v221
	v_and_b32_e32 v75, 0xffff0000, v221
	v_lshlrev_b32_e32 v76, 16, v222
	v_and_b32_e32 v77, 0xffff0000, v222
	v_lshlrev_b32_e32 v78, 16, v223
	v_and_b32_e32 v79, 0xffff0000, v223
	v_pk_fma_f32 v[70:71], v[70:71], v[126:127], v[74:75]
	v_pk_fma_f32 v[68:69], v[68:69], v[124:125], v[72:73]
	v_pk_fma_f32 v[72:73], v[66:67], v[122:123], v[78:79]
	v_pk_fma_f32 v[66:67], v[64:65], v[120:121], v[76:77]
	v_cvt_pk_bf16_f32 v64, v68, v69
	v_cvt_pk_bf16_f32 v65, v70, v71
	s_nop 0
	v_cvt_pk_bf16_f32 v66, v66, v67
	v_cvt_pk_bf16_f32 v67, v72, v73
	s_nop 0
	global_store_dwordx4 v[96:97], v[64:67], off offset:256
	s_nop 0
	s_nop 0
	v_lshlrev_b32_e32 v64, 16, v224
	v_and_b32_e32 v65, 0xffff0000, v224
	v_lshlrev_b32_e32 v66, 16, v225
	v_and_b32_e32 v67, 0xffff0000, v225
	v_lshlrev_b32_e32 v68, 16, v226
	v_and_b32_e32 v69, 0xffff0000, v226
	v_lshlrev_b32_e32 v70, 16, v227
	v_and_b32_e32 v71, 0xffff0000, v227
	v_pk_fma_f32 v[62:63], v[62:63], v[142:143], v[66:67]
	v_pk_fma_f32 v[60:61], v[60:61], v[140:141], v[64:65]
	v_pk_fma_f32 v[64:65], v[58:59], v[138:139], v[70:71]
	v_pk_fma_f32 v[58:59], v[56:57], v[136:137], v[68:69]
	v_cvt_pk_bf16_f32 v56, v60, v61
	v_cvt_pk_bf16_f32 v57, v62, v63
	s_nop 0
	v_cvt_pk_bf16_f32 v58, v58, v59
	v_cvt_pk_bf16_f32 v59, v64, v65
	v_lshl_add_u64 v[64:65], s[18:19], 0, v[156:157]
	global_store_dwordx4 v[80:81], v[56:59], off
	v_lshl_add_u64 v[64:65], v[64:65], 0, v[176:177]
	s_nop 0
	v_lshlrev_b32_e32 v56, 16, v228
	v_and_b32_e32 v57, 0xffff0000, v228
	v_lshlrev_b32_e32 v58, 16, v229
	v_and_b32_e32 v59, 0xffff0000, v229
	v_lshlrev_b32_e32 v60, 16, v230
	v_and_b32_e32 v61, 0xffff0000, v230
	v_lshlrev_b32_e32 v62, 16, v231
	v_and_b32_e32 v63, 0xffff0000, v231
	v_pk_fma_f32 v[50:51], v[50:51], v[126:127], v[58:59]
	v_pk_fma_f32 v[48:49], v[48:49], v[124:125], v[56:57]
	v_pk_fma_f32 v[56:57], v[46:47], v[122:123], v[62:63]
	v_pk_fma_f32 v[46:47], v[44:45], v[120:121], v[60:61]
; __device__ __forceinline__ unsigned cvt_pk_bf16(float lo, float hi) { unsigned r; asm volatile("v_cvt_pk_bf16_f32 %0, %1, %2" : "=v"(r) : "v"(lo), "v"(hi)); return r; }
; __device__ __forceinline__ void ld8(const bf16_t* p, f32x4& a, f32x4& b) { const u32x4 r = *(const u32x4*)p;
;     a = (f32x4){__uint_as_float(r.x << 16), __uint_as_float(r.x & 0xffff0000u), __uint_as_float(r.y << 16), __uint_as_float(r.y & 0xffff0000u)};
;     b = (f32x4){__uint_as_float(r.z << 16), __uint_as_float(r.z & 0xffff0000u), __uint_as_float(r.w << 16), __uint_as_float(r.w & 0xffff0000u)}; }
; __device__ __forceinline__ void st8(bf16_t* p, f32x4 a, f32x4 b) { u32x4 w; w.x = cvt_pk_bf16(a[0], a[1]); w.y = cvt_pk_bf16(a[2], a[3]); w.z = cvt_pk_bf16(b[0], b[1]); w.w = cvt_pk_bf16(b[2], b[3]); *(u32x4*)p = w; }
;     __device__ __forceinline__ void operator()(const f32x4 (&acc)[2][2][4][2], const Unit& u, int wr, int wc, int fr, int fq) const {
;     ...
;             for (int n = 0; n < 2; ++n) gv[bj][n] = *(const f32x4*)(gp + col0 + bj * HALF + 4 * n);
; #pragma unroll
;         for (int ai = 0; ai < 2; ++ai)
; #pragma unroll
;             for (int m = 0; m < 4; ++m) { const size_t ro = (size_t)(wr * 64 + fr + ai * HALF + m * 16) * 1024 + col0;
; #pragma unroll
;                 for (int bj = 0; bj < 2; ++bj) {
;                     f32x4 r0, r1; ld8(rb + ro + bj * HALF, r0, r1);
;                     st8(ob + ro + bj * HALF, r0 + gv[bj][0] * acc[ai][bj][m][0], r1 + gv[bj][1] * acc[ai][bj][m][1]); } }
	v_cvt_pk_bf16_f32 v44, v48, v49
	v_cvt_pk_bf16_f32 v45, v50, v51
	s_nop 0
	v_cvt_pk_bf16_f32 v46, v46, v47
	v_cvt_pk_bf16_f32 v47, v56, v57
	s_nop 0
	global_store_dwordx4 v[80:81], v[44:47], off offset:256
	s_nop 0
	s_nop 0
	v_lshlrev_b32_e32 v44, 16, v240
	v_and_b32_e32 v45, 0xffff0000, v240
	v_lshlrev_b32_e32 v46, 16, v241
	v_and_b32_e32 v47, 0xffff0000, v241
	v_lshlrev_b32_e32 v48, 16, v242
	v_and_b32_e32 v49, 0xffff0000, v242
	v_lshlrev_b32_e32 v50, 16, v243
	v_and_b32_e32 v51, 0xffff0000, v243
	v_pk_fma_f32 v[46:47], v[54:55], v[142:143], v[46:47]
	v_pk_fma_f32 v[44:45], v[52:53], v[140:141], v[44:45]
	v_pk_fma_f32 v[50:51], v[42:43], v[138:139], v[50:51]
	v_pk_fma_f32 v[42:43], v[40:41], v[136:137], v[48:49]
	v_cvt_pk_bf16_f32 v40, v44, v45
	v_cvt_pk_bf16_f32 v41, v46, v47
	v_lshl_add_u64 v[48:49], s[18:19], 0, v[158:159]
	v_cvt_pk_bf16_f32 v42, v42, v43
	v_cvt_pk_bf16_f32 v43, v50, v51
	v_lshl_add_u64 v[48:49], v[48:49], 0, v[176:177]
	global_store_dwordx4 v[64:65], v[40:43], off
	s_nop 0
	s_nop 0
	v_lshlrev_b32_e32 v40, 16, v244
	v_and_b32_e32 v41, 0xffff0000, v244
	v_lshlrev_b32_e32 v42, 16, v245
	v_and_b32_e32 v43, 0xffff0000, v245
	v_lshlrev_b32_e32 v44, 16, v246
	v_and_b32_e32 v45, 0xffff0000, v246
	v_lshlrev_b32_e32 v46, 16, v247
	v_and_b32_e32 v47, 0xffff0000, v247
	v_pk_fma_f32 v[34:35], v[34:35], v[126:127], v[42:43]
	v_pk_fma_f32 v[32:33], v[32:33], v[124:125], v[40:41]
	v_pk_fma_f32 v[40:41], v[30:31], v[122:123], v[46:47]
	v_pk_fma_f32 v[30:31], v[28:29], v[120:121], v[44:45]
	v_cvt_pk_bf16_f32 v28, v32, v33
	v_cvt_pk_bf16_f32 v29, v34, v35
	s_nop 0
	v_cvt_pk_bf16_f32 v30, v30, v31
	v_cvt_pk_bf16_f32 v31, v40, v41
	s_nop 0
	global_store_dwordx4 v[64:65], v[28:31], off offset:256
	s_nop 0
	s_nop 0
	v_lshlrev_b32_e32 v28, 16, v248
	v_and_b32_e32 v29, 0xffff0000, v248
	v_lshlrev_b32_e32 v30, 16, v249
	v_and_b32_e32 v31, 0xffff0000, v249
	v_lshlrev_b32_e32 v32, 16, v250
	v_and_b32_e32 v33, 0xffff0000, v250
	v_lshlrev_b32_e32 v34, 16, v251
	v_and_b32_e32 v35, 0xffff0000, v251
	v_pk_fma_f32 v[30:31], v[38:39], v[142:143], v[30:31]
	v_pk_fma_f32 v[28:29], v[36:37], v[140:141], v[28:29]
	v_pk_fma_f32 v[34:35], v[26:27], v[138:139], v[34:35]
	v_pk_fma_f32 v[26:27], v[24:25], v[136:137], v[32:33]
	v_cvt_pk_bf16_f32 v24, v28, v29
	v_cvt_pk_bf16_f32 v25, v30, v31
	v_lshl_add_u64 v[32:33], s[18:19], 0, v[160:161]
	v_cvt_pk_bf16_f32 v26, v26, v27
	v_cvt_pk_bf16_f32 v27, v34, v35
	v_lshl_add_u64 v[32:33], v[32:33], 0, v[176:177]
	global_store_dwordx4 v[48:49], v[24:27], off
	s_nop 0
	s_nop 0
	s_waitcnt vmcnt(14)
	v_lshlrev_b32_e32 v24, 16, v196
	v_and_b32_e32 v25, 0xffff0000, v196
	v_lshlrev_b32_e32 v26, 16, v197
	v_and_b32_e32 v27, 0xffff0000, v197
	v_lshlrev_b32_e32 v28, 16, v198
	v_and_b32_e32 v29, 0xffff0000, v198
	v_lshlrev_b32_e32 v30, 16, v199
	v_and_b32_e32 v31, 0xffff0000, v199
	v_pk_fma_f32 v[18:19], v[18:19], v[126:127], v[26:27]
	v_pk_fma_f32 v[16:17], v[16:17], v[124:125], v[24:25]
	v_pk_fma_f32 v[24:25], v[14:15], v[122:123], v[30:31]
	v_pk_fma_f32 v[14:15], v[12:13], v[120:121], v[28:29]
	v_cvt_pk_bf16_f32 v12, v16, v17
	v_cvt_pk_bf16_f32 v13, v18, v19
	s_nop 0
	v_cvt_pk_bf16_f32 v14, v14, v15
	v_cvt_pk_bf16_f32 v15, v24, v25
	s_nop 0
	global_store_dwordx4 v[48:49], v[12:15], off offset:256
	s_nop 0
	s_nop 0
	s_waitcnt vmcnt(13)
	v_lshlrev_b32_e32 v12, 16, v200
	v_and_b32_e32 v13, 0xffff0000, v200
	v_lshlrev_b32_e32 v14, 16, v201
	v_and_b32_e32 v15, 0xffff0000, v201
	v_lshlrev_b32_e32 v16, 16, v202
	v_and_b32_e32 v17, 0xffff0000, v202
	v_lshlrev_b32_e32 v18, 16, v203
	v_and_b32_e32 v19, 0xffff0000, v203
	v_pk_fma_f32 v[14:15], v[22:23], v[142:143], v[14:15]
	v_pk_fma_f32 v[12:13], v[20:21], v[140:141], v[12:13]
	v_pk_fma_f32 v[18:19], v[10:11], v[138:139], v[18:19]
	v_pk_fma_f32 v[10:11], v[8:9], v[136:137], v[16:17]
	v_cvt_pk_bf16_f32 v8, v12, v13
	v_cvt_pk_bf16_f32 v9, v14, v15
	s_nop 0
	v_cvt_pk_bf16_f32 v10, v10, v11
	v_cvt_pk_bf16_f32 v11, v18, v19
	s_nop 0
	global_store_dwordx4 v[32:33], v[8:11], off
	s_nop 0
	s_nop 0
	s_waitcnt vmcnt(12)
	v_lshlrev_b32_e32 v8, 16, v204
	v_and_b32_e32 v9, 0xffff0000, v204
	v_lshlrev_b32_e32 v10, 16, v205
	v_and_b32_e32 v11, 0xffff0000, v205
	v_lshlrev_b32_e32 v12, 16, v206
	v_and_b32_e32 v13, 0xffff0000, v206
	v_lshlrev_b32_e32 v14, 16, v207
	v_and_b32_e32 v15, 0xffff0000, v207
	v_pk_fma_f32 v[4:5], v[4:5], v[124:125], v[8:9]
	v_pk_fma_f32 v[8:9], v[2:3], v[122:123], v[14:15]
	v_pk_fma_f32 v[2:3], v[0:1], v[120:121], v[12:13]
	v_pk_fma_f32 v[6:7], v[6:7], v[126:127], v[10:11]
	v_cvt_pk_bf16_f32 v0, v4, v5
	s_nop 0
	v_cvt_pk_bf16_f32 v1, v6, v7
	v_cvt_pk_bf16_f32 v2, v2, v3
	v_cvt_pk_bf16_f32 v3, v8, v9
	global_store_dwordx4 v[32:33], v[0:3], off offset:256
	s_cbranch_vccnz .LBB0_977
	s_andn2_b64 vcc, exec, s[10:11]
	s_cbranch_vccnz .LBB0_976
	s_barrier
	s_branch .LBB0_976

; __device__ __forceinline__ unsigned cvt_pk_bf16(float lo, float hi) { unsigned r; asm volatile("v_cvt_pk_bf16_f32 %0, %1, %2" : "=v"(r) : "v"(lo), "v"(hi)); return r; }
; __device__ __forceinline__ void ld8(const bf16_t* p, f32x4& a, f32x4& b) { const u32x4 r = *(const u32x4*)p;
;     a = (f32x4){__uint_as_float(r.x << 16), __uint_as_float(r.x & 0xffff0000u), __uint_as_float(r.y << 16), __uint_as_float(r.y & 0xffff0000u)};
;     b = (f32x4){__uint_as_float(r.z << 16), __uint_as_float(r.z & 0xffff0000u), __uint_as_float(r.w << 16), __uint_as_float(r.w & 0xffff0000u)}; }
; __device__ __forceinline__ void st8(bf16_t* p, f32x4 a, f32x4 b) { u32x4 w; w.x = cvt_pk_bf16(a[0], a[1]); w.y = cvt_pk_bf16(a[2], a[3]); w.z = cvt_pk_bf16(b[0], b[1]); w.w = cvt_pk_bf16(b[2], b[3]); *(u32x4*)p = w; }
;     __device__ __forceinline__ void operator()(const f32x4 (&acc)[2][2][4][2], const Unit& u, int wr, int wc, int fr, int fq) const {
;         const int b = u.pm / 65, w = u.pm % 65;
;         const RT* rb; OT* ob; const float* gp;
;         if (w == 0) { rb = res_ctx + (size_t)b * 256 * 1024; ob = out_ctx + (size_t)b * 256 * 1024; gp = gate + 2 * 6144; }
;         else { const size_t o = ((size_t)b * 16384 + (size_t)(w - 1) * 256) * 1024; rb = res_lat + o; ob = out_lat + o; gp = gate + b * 6144; }
;         const int col0 = u.pn * BM + wc * 32 + 8 * fq;
;         f32x4 gv[2][2];
; #pragma unroll
;         for (int bj = 0; bj < 2; ++bj)
; #pragma unroll
;             for (int n = 0; n < 2; ++n) gv[bj][n] = *(const f32x4*)(gp + col0 + bj * HALF + 4 * n);
; #pragma unroll
;         for (int ai = 0; ai < 2; ++ai)
; #pragma unroll
;             for (int m = 0; m < 4; ++m) { const size_t ro = (size_t)(wr * 64 + fr + ai * HALF + m * 16) * 1024 + col0;
; #pragma unroll
;                 for (int bj = 0; bj < 2; ++bj) {
;                     f32x4 r0, r1; ld8(rb + ro + bj * HALF, r0, r1);
;                     st8(ob + ro + bj * HALF, r0 + gv[bj][0] * acc[ai][bj][m][0], r1 + gv[bj][1] * acc[ai][bj][m][1]); } }
.LBB0_1581:
	v_lshl_or_b32 v120, s54, 8, v179
	v_ashrrev_i32_e32 v121, 31, v120
	v_lshl_add_u64 v[122:123], s[20:21], 0, v[152:153]
	v_lshlrev_b64 v[176:177], 1, v[120:121]
	v_lshl_add_u64 v[188:189], v[122:123], 0, v[176:177]
	global_load_dwordx4 v[184:187], v[188:189], off
	v_lshl_add_u64 v[124:125], v[120:121], 2, s[24:25]
	global_load_dwordx4 v[140:143], v[124:125], off
	global_load_dwordx4 v[136:139], v[124:125], off offset:16
	global_load_dwordx4 v[120:123], v[124:125], off offset:528
	s_nop 0
	global_load_dwordx4 v[124:127], v[124:125], off offset:512
	s_andn2_b64 vcc, exec, s[0:1]
	s_mov_b64 s[0:1], -1
	global_load_dwordx4 v[196:199], v[188:189], off offset:256
	v_lshl_add_u64 v[194:195], s[20:21], 0, v[162:163]
	v_lshl_add_u64 v[194:195], v[194:195], 0, v[176:177]
	global_load_dwordx4 v[200:203], v[194:195], off
	v_lshl_add_u64 v[194:195], s[20:21], 0, v[162:163]
	v_lshl_add_u64 v[194:195], v[194:195], 0, v[176:177]
	global_load_dwordx4 v[204:207], v[194:195], off offset:256
	v_lshl_add_u64 v[194:195], s[20:21], 0, v[164:165]
	v_lshl_add_u64 v[194:195], v[194:195], 0, v[176:177]
	global_load_dwordx4 v[208:211], v[194:195], off
	v_lshl_add_u64 v[194:195], s[20:21], 0, v[164:165]
	v_lshl_add_u64 v[194:195], v[194:195], 0, v[176:177]
	global_load_dwordx4 v[212:215], v[194:195], off offset:256
	v_lshl_add_u64 v[194:195], s[20:21], 0, v[166:167]
	v_lshl_add_u64 v[194:195], v[194:195], 0, v[176:177]
	global_load_dwordx4 v[216:219], v[194:195], off
	v_lshl_add_u64 v[194:195], s[20:21], 0, v[166:167]
	v_lshl_add_u64 v[194:195], v[194:195], 0, v[176:177]
	global_load_dwordx4 v[220:223], v[194:195], off offset:256
	v_lshl_add_u64 v[194:195], s[20:21], 0, v[154:155]
	v_lshl_add_u64 v[194:195], v[194:195], 0, v[176:177]
	global_load_dwordx4 v[224:227], v[194:195], off
	v_lshl_add_u64 v[194:195], s[20:21], 0, v[154:155]
	v_lshl_add_u64 v[194:195], v[194:195], 0, v[176:177]
	global_load_dwordx4 v[228:231], v[194:195], off offset:256
	v_lshl_add_u64 v[194:195], s[20:21], 0, v[156:157]
	v_lshl_add_u64 v[194:195], v[194:195], 0, v[176:177]
	global_load_dwordx4 v[240:243], v[194:195], off
	v_lshl_add_u64 v[194:195], s[20:21], 0, v[156:157]
	v_lshl_add_u64 v[194:195], v[194:195], 0, v[176:177]
	global_load_dwordx4 v[244:247], v[194:195], off offset:256
	v_lshl_add_u64 v[194:195], s[20:21], 0, v[158:159]
	v_lshl_add_u64 v[194:195], v[194:195], 0, v[176:177]
	global_load_dwordx4 v[248:251], v[194:195], off
	s_waitcnt vmcnt(0)
	v_lshlrev_b32_e32 v190, 16, v184
	v_and_b32_e32 v191, 0xffff0000, v184
	v_lshlrev_b32_e32 v184, 16, v185
	v_and_b32_e32 v185, 0xffff0000, v185
	v_lshlrev_b32_e32 v192, 16, v186
	v_and_b32_e32 v193, 0xffff0000, v186
	v_lshlrev_b32_e32 v186, 16, v187
	v_and_b32_e32 v187, 0xffff0000, v187
	v_pk_fma_f32 v[134:135], v[134:135], v[142:143], v[184:185]
	v_pk_fma_f32 v[132:133], v[132:133], v[140:141], v[190:191]
	v_pk_fma_f32 v[184:185], v[130:131], v[138:139], v[186:187]
	v_pk_fma_f32 v[130:131], v[128:129], v[136:137], v[192:193]
	v_cvt_pk_bf16_f32 v128, v132, v133
	v_cvt_pk_bf16_f32 v129, v134, v135
	s_nop 0
	v_cvt_pk_bf16_f32 v130, v130, v131
	v_cvt_pk_bf16_f32 v131, v184, v185
	v_lshl_add_u64 v[184:185], s[20:21], 0, v[162:163]
	global_store_dwordx4 v[188:189], v[128:131], off
	v_lshl_add_u64 v[184:185], v[184:185], 0, v[176:177]
	s_nop 0
	v_lshlrev_b32_e32 v128, 16, v196
	v_and_b32_e32 v129, 0xffff0000, v196
	v_lshlrev_b32_e32 v130, 16, v197
	v_and_b32_e32 v131, 0xffff0000, v197
	v_lshlrev_b32_e32 v132, 16, v198
	v_and_b32_e32 v133, 0xffff0000, v198
	v_lshlrev_b32_e32 v134, 16, v199
	v_and_b32_e32 v135, 0xffff0000, v199
	v_lshl_add_u64 v[194:195], s[20:21], 0, v[158:159]
	v_lshl_add_u64 v[194:195], v[194:195], 0, v[176:177]
	global_load_dwordx4 v[196:199], v[194:195], off offset:256
	v_pk_fma_f32 v[114:115], v[114:115], v[126:127], v[130:131]
	v_pk_fma_f32 v[112:113], v[112:113], v[124:125], v[128:129]
	v_pk_fma_f32 v[128:129], v[110:111], v[122:123], v[134:135]
	v_pk_fma_f32 v[110:111], v[108:109], v[120:121], v[132:133]
	v_cvt_pk_bf16_f32 v108, v112, v113
	v_cvt_pk_bf16_f32 v109, v114, v115
	s_nop 0
	v_cvt_pk_bf16_f32 v110, v110, v111
	v_cvt_pk_bf16_f32 v111, v128, v129
	s_nop 0
	global_store_dwordx4 v[188:189], v[108:111], off offset:256
	s_nop 0
	s_nop 0
	v_lshlrev_b32_e32 v108, 16, v200
	v_and_b32_e32 v109, 0xffff0000, v200
	v_lshlrev_b32_e32 v110, 16, v201
	v_and_b32_e32 v111, 0xffff0000, v201
	v_lshlrev_b32_e32 v112, 16, v202
	v_and_b32_e32 v113, 0xffff0000, v202
	v_lshlrev_b32_e32 v114, 16, v203
	v_and_b32_e32 v115, 0xffff0000, v203
	v_lshl_add_u64 v[194:195], s[20:21], 0, v[160:161]
	v_lshl_add_u64 v[194:195], v[194:195], 0, v[176:177]
	global_load_dwordx4 v[200:203], v[194:195], off
	v_pk_fma_f32 v[110:111], v[118:119], v[142:143], v[110:111]
	v_pk_fma_f32 v[108:109], v[116:117], v[140:141], v[108:109]
	v_pk_fma_f32 v[114:115], v[106:107], v[138:139], v[114:115]
	v_pk_fma_f32 v[106:107], v[104:105], v[136:137], v[112:113]
	v_cvt_pk_bf16_f32 v104, v108, v109
	v_cvt_pk_bf16_f32 v105, v110, v111
	v_lshl_add_u64 v[112:113], s[20:21], 0, v[164:165]
	v_cvt_pk_bf16_f32 v106, v106, v107
	v_cvt_pk_bf16_f32 v107, v114, v115
	v_lshl_add_u64 v[112:113], v[112:113], 0, v[176:177]
	global_store_dwordx4 v[184:185], v[104:107], off
	s_nop 0
	s_nop 0
	v_lshlrev_b32_e32 v104, 16, v204
	v_and_b32_e32 v105, 0xffff0000, v204
	v_lshlrev_b32_e32 v106, 16, v205
	v_and_b32_e32 v107, 0xffff0000, v205
	v_lshlrev_b32_e32 v108, 16, v206
	v_and_b32_e32 v109, 0xffff0000, v206
	v_lshlrev_b32_e32 v110, 16, v207
	v_and_b32_e32 v111, 0xffff0000, v207
	v_lshl_add_u64 v[194:195], s[20:21], 0, v[160:161]
	v_lshl_add_u64 v[194:195], v[194:195], 0, v[176:177]
; __device__ __forceinline__ unsigned cvt_pk_bf16(float lo, float hi) { unsigned r; asm volatile("v_cvt_pk_bf16_f32 %0, %1, %2" : "=v"(r) : "v"(lo), "v"(hi)); return r; }
; __device__ __forceinline__ void ld8(const bf16_t* p, f32x4& a, f32x4& b) { const u32x4 r = *(const u32x4*)p;
;     a = (f32x4){__uint_as_float(r.x << 16), __uint_as_float(r.x & 0xffff0000u), __uint_as_float(r.y << 16), __uint_as_float(r.y & 0xffff0000u)};
;     b = (f32x4){__uint_as_float(r.z << 16), __uint_as_float(r.z & 0xffff0000u), __uint_as_float(r.w << 16), __uint_as_float(r.w & 0xffff0000u)}; }
; __device__ __forceinline__ void st8(bf16_t* p, f32x4 a, f32x4 b) { u32x4 w; w.x = cvt_pk_bf16(a[0], a[1]); w.y = cvt_pk_bf16(a[2], a[3]); w.z = cvt_pk_bf16(b[0], b[1]); w.w = cvt_pk_bf16(b[2], b[3]); *(u32x4*)p = w; }
;     __device__ __forceinline__ void operator()(const f32x4 (&acc)[2][2][4][2], const Unit& u, int wr, int wc, int fr, int fq) const {
;     ...
;             for (int n = 0; n < 2; ++n) gv[bj][n] = *(const f32x4*)(gp + col0 + bj * HALF + 4 * n);
; #pragma unroll
;         for (int ai = 0; ai < 2; ++ai)
; #pragma unroll
;             for (int m = 0; m < 4; ++m) { const size_t ro = (size_t)(wr * 64 + fr + ai * HALF + m * 16) * 1024 + col0;
; #pragma unroll
;                 for (int bj = 0; bj < 2; ++bj) {
;                     f32x4 r0, r1; ld8(rb + ro + bj * HALF, r0, r1);
;                     st8(ob + ro + bj * HALF, r0 + gv[bj][0] * acc[ai][bj][m][0], r1 + gv[bj][1] * acc[ai][bj][m][1]); } }
	global_load_dwordx4 v[204:207], v[194:195], off offset:256
	v_pk_fma_f32 v[98:99], v[98:99], v[126:127], v[106:107]
	v_pk_fma_f32 v[96:97], v[96:97], v[124:125], v[104:105]
	v_pk_fma_f32 v[104:105], v[94:95], v[122:123], v[110:111]
	v_pk_fma_f32 v[94:95], v[92:93], v[120:121], v[108:109]
	v_cvt_pk_bf16_f32 v92, v96, v97
	v_cvt_pk_bf16_f32 v93, v98, v99
	s_nop 0
	v_cvt_pk_bf16_f32 v94, v94, v95
	v_cvt_pk_bf16_f32 v95, v104, v105
	s_nop 0
	global_store_dwordx4 v[184:185], v[92:95], off offset:256
	s_nop 0
	s_nop 0
	v_lshlrev_b32_e32 v92, 16, v208
	v_and_b32_e32 v93, 0xffff0000, v208
	v_lshlrev_b32_e32 v94, 16, v209
	v_and_b32_e32 v95, 0xffff0000, v209
	v_lshlrev_b32_e32 v96, 16, v210
	v_and_b32_e32 v97, 0xffff0000, v210
	v_lshlrev_b32_e32 v98, 16, v211
	v_and_b32_e32 v99, 0xffff0000, v211
	v_pk_fma_f32 v[94:95], v[102:103], v[142:143], v[94:95]
	v_pk_fma_f32 v[92:93], v[100:101], v[140:141], v[92:93]
	v_pk_fma_f32 v[98:99], v[90:91], v[138:139], v[98:99]
	v_pk_fma_f32 v[90:91], v[88:89], v[136:137], v[96:97]
	v_cvt_pk_bf16_f32 v88, v92, v93
	v_cvt_pk_bf16_f32 v89, v94, v95
	v_lshl_add_u64 v[96:97], s[20:21], 0, v[166:167]
	v_cvt_pk_bf16_f32 v90, v90, v91
	v_cvt_pk_bf16_f32 v91, v98, v99
	v_lshl_add_u64 v[96:97], v[96:97], 0, v[176:177]
	global_store_dwordx4 v[112:113], v[88:91], off
	s_nop 0
	s_nop 0
	v_lshlrev_b32_e32 v88, 16, v212
	v_and_b32_e32 v89, 0xffff0000, v212
	v_lshlrev_b32_e32 v90, 16, v213
	v_and_b32_e32 v91, 0xffff0000, v213
	v_lshlrev_b32_e32 v92, 16, v214
	v_and_b32_e32 v93, 0xffff0000, v214
	v_lshlrev_b32_e32 v94, 16, v215
	v_and_b32_e32 v95, 0xffff0000, v215
	v_pk_fma_f32 v[82:83], v[82:83], v[126:127], v[90:91]
	v_pk_fma_f32 v[80:81], v[80:81], v[124:125], v[88:89]
	v_pk_fma_f32 v[88:89], v[78:79], v[122:123], v[94:95]
	v_pk_fma_f32 v[78:79], v[76:77], v[120:121], v[92:93]
	v_cvt_pk_bf16_f32 v76, v80, v81
	v_cvt_pk_bf16_f32 v77, v82, v83
	s_nop 0
	v_cvt_pk_bf16_f32 v78, v78, v79
	v_cvt_pk_bf16_f32 v79, v88, v89
	s_nop 0
	global_store_dwordx4 v[112:113], v[76:79], off offset:256
	s_nop 0
	s_nop 0
	v_lshlrev_b32_e32 v76, 16, v216
	v_and_b32_e32 v77, 0xffff0000, v216
	v_lshlrev_b32_e32 v78, 16, v217
	v_and_b32_e32 v79, 0xffff0000, v217
	v_lshlrev_b32_e32 v80, 16, v218
	v_and_b32_e32 v81, 0xffff0000, v218
	v_lshlrev_b32_e32 v82, 16, v219
	v_and_b32_e32 v83, 0xffff0000, v219
	v_pk_fma_f32 v[78:79], v[86:87], v[142:143], v[78:79]
	v_pk_fma_f32 v[76:77], v[84:85], v[140:141], v[76:77]
	v_pk_fma_f32 v[82:83], v[74:75], v[138:139], v[82:83]
	v_pk_fma_f32 v[74:75], v[72:73], v[136:137], v[80:81]
	v_cvt_pk_bf16_f32 v72, v76, v77
	v_cvt_pk_bf16_f32 v73, v78, v79
	v_lshl_add_u64 v[80:81], s[20:21], 0, v[154:155]
	v_cvt_pk_bf16_f32 v74, v74, v75
	v_cvt_pk_bf16_f32 v75, v82, v83
	v_lshl_add_u64 v[80:81], v[80:81], 0, v[176:177]
	global_store_dwordx4 v[96:97], v[72:75], off
	s_nop 0
	s_nop 0
	v_lshlrev_b32_e32 v72, 16, v220
	v_and_b32_e32 v73, 0xffff0000, v220
	v_lshlrev_b32_e32 v74, 16, v221
	v_and_b32_e32 v75, 0xffff0000, v221
	v_lshlrev_b32_e32 v76, 16, v222
	v_and_b32_e32 v77, 0xffff0000, v222
	v_lshlrev_b32_e32 v78, 16, v223
	v_and_b32_e32 v79, 0xffff0000, v223
	v_pk_fma_f32 v[70:71], v[70:71], v[126:127], v[74:75]
	v_pk_fma_f32 v[68:69], v[68:69], v[124:125], v[72:73]
	v_pk_fma_f32 v[72:73], v[66:67], v[122:123], v[78:79]
	v_pk_fma_f32 v[66:67], v[64:65], v[120:121], v[76:77]
	v_cvt_pk_bf16_f32 v64, v68, v69
	v_cvt_pk_bf16_f32 v65, v70, v71
	s_nop 0
	v_cvt_pk_bf16_f32 v66, v66, v67
	v_cvt_pk_bf16_f32 v67, v72, v73
	s_nop 0
	global_store_dwordx4 v[96:97], v[64:67], off offset:256
	s_nop 0
	s_nop 0
	v_lshlrev_b32_e32 v64, 16, v224
	v_and_b32_e32 v65, 0xffff0000, v224
	v_lshlrev_b32_e32 v66, 16, v225
	v_and_b32_e32 v67, 0xffff0000, v225
	v_lshlrev_b32_e32 v68, 16, v226
	v_and_b32_e32 v69, 0xffff0000, v226
	v_lshlrev_b32_e32 v70, 16, v227
	v_and_b32_e32 v71, 0xffff0000, v227
	v_pk_fma_f32 v[62:63], v[62:63], v[142:143], v[66:67]
	v_pk_fma_f32 v[60:61], v[60:61], v[140:141], v[64:65]
	v_pk_fma_f32 v[64:65], v[58:59], v[138:139], v[70:71]
	v_pk_fma_f32 v[58:59], v[56:57], v[136:137], v[68:69]
	v_cvt_pk_bf16_f32 v56, v60, v61
	v_cvt_pk_bf16_f32 v57, v62, v63
	s_nop 0
	v_cvt_pk_bf16_f32 v58, v58, v59
	v_cvt_pk_bf16_f32 v59, v64, v65
	v_lshl_add_u64 v[64:65], s[20:21], 0, v[156:157]
	global_store_dwordx4 v[80:81], v[56:59], off
	v_lshl_add_u64 v[64:65], v[64:65], 0, v[176:177]
	s_nop 0
	v_lshlrev_b32_e32 v56, 16, v228
	v_and_b32_e32 v57, 0xffff0000, v228
	v_lshlrev_b32_e32 v58, 16, v229
	v_and_b32_e32 v59, 0xffff0000, v229
	v_lshlrev_b32_e32 v60, 16, v230
	v_and_b32_e32 v61, 0xffff0000, v230
	v_lshlrev_b32_e32 v62, 16, v231
	v_and_b32_e32 v63, 0xffff0000, v231
	v_pk_fma_f32 v[50:51], v[50:51], v[126:127], v[58:59]
	v_pk_fma_f32 v[48:49], v[48:49], v[124:125], v[56:57]
	v_pk_fma_f32 v[56:57], v[46:47], v[122:123], v[62:63]
	v_pk_fma_f32 v[46:47], v[44:45], v[120:121], v[60:61]
; __device__ __forceinline__ unsigned cvt_pk_bf16(float lo, float hi) { unsigned r; asm volatile("v_cvt_pk_bf16_f32 %0, %1, %2" : "=v"(r) : "v"(lo), "v"(hi)); return r; }
; __device__ __forceinline__ void ld8(const bf16_t* p, f32x4& a, f32x4& b) { const u32x4 r = *(const u32x4*)p;
;     a = (f32x4){__uint_as_float(r.x << 16), __uint_as_float(r.x & 0xffff0000u), __uint_as_float(r.y << 16), __uint_as_float(r.y & 0xffff0000u)};
;     b = (f32x4){__uint_as_float(r.z << 16), __uint_as_float(r.z & 0xffff0000u), __uint_as_float(r.w << 16), __uint_as_float(r.w & 0xffff0000u)}; }
; __device__ __forceinline__ void st8(bf16_t* p, f32x4 a, f32x4 b) { u32x4 w; w.x = cvt_pk_bf16(a[0], a[1]); w.y = cvt_pk_bf16(a[2], a[3]); w.z = cvt_pk_bf16(b[0], b[1]); w.w = cvt_pk_bf16(b[2], b[3]); *(u32x4*)p = w; }
;     __device__ __forceinline__ void operator()(const f32x4 (&acc)[2][2][4][2], const Unit& u, int wr, int wc, int fr, int fq) const {
;     ...
;             for (int n = 0; n < 2; ++n) gv[bj][n] = *(const f32x4*)(gp + col0 + bj * HALF + 4 * n);
; #pragma unroll
;         for (int ai = 0; ai < 2; ++ai)
; #pragma unroll
;             for (int m = 0; m < 4; ++m) { const size_t ro = (size_t)(wr * 64 + fr + ai * HALF + m * 16) * 1024 + col0;
; #pragma unroll
;                 for (int bj = 0; bj < 2; ++bj) {
;                     f32x4 r0, r1; ld8(rb + ro + bj * HALF, r0, r1);
;                     st8(ob + ro + bj * HALF, r0 + gv[bj][0] * acc[ai][bj][m][0], r1 + gv[bj][1] * acc[ai][bj][m][1]); } }
	v_cvt_pk_bf16_f32 v44, v48, v49
	v_cvt_pk_bf16_f32 v45, v50, v51
	s_nop 0
	v_cvt_pk_bf16_f32 v46, v46, v47
	v_cvt_pk_bf16_f32 v47, v56, v57
	s_nop 0
	global_store_dwordx4 v[80:81], v[44:47], off offset:256
	s_nop 0
	s_nop 0
	v_lshlrev_b32_e32 v44, 16, v240
	v_and_b32_e32 v45, 0xffff0000, v240
	v_lshlrev_b32_e32 v46, 16, v241
	v_and_b32_e32 v47, 0xffff0000, v241
	v_lshlrev_b32_e32 v48, 16, v242
	v_and_b32_e32 v49, 0xffff0000, v242
	v_lshlrev_b32_e32 v50, 16, v243
	v_and_b32_e32 v51, 0xffff0000, v243
	v_pk_fma_f32 v[46:47], v[54:55], v[142:143], v[46:47]
	v_pk_fma_f32 v[44:45], v[52:53], v[140:141], v[44:45]
	v_pk_fma_f32 v[50:51], v[42:43], v[138:139], v[50:51]
	v_pk_fma_f32 v[42:43], v[40:41], v[136:137], v[48:49]
	v_cvt_pk_bf16_f32 v40, v44, v45
	v_cvt_pk_bf16_f32 v41, v46, v47
	v_lshl_add_u64 v[48:49], s[20:21], 0, v[158:159]
	v_cvt_pk_bf16_f32 v42, v42, v43
	v_cvt_pk_bf16_f32 v43, v50, v51
	v_lshl_add_u64 v[48:49], v[48:49], 0, v[176:177]
	global_store_dwordx4 v[64:65], v[40:43], off
	s_nop 0
	s_nop 0
	v_lshlrev_b32_e32 v40, 16, v244
	v_and_b32_e32 v41, 0xffff0000, v244
	v_lshlrev_b32_e32 v42, 16, v245
	v_and_b32_e32 v43, 0xffff0000, v245
	v_lshlrev_b32_e32 v44, 16, v246
	v_and_b32_e32 v45, 0xffff0000, v246
	v_lshlrev_b32_e32 v46, 16, v247
	v_and_b32_e32 v47, 0xffff0000, v247
	v_pk_fma_f32 v[34:35], v[34:35], v[126:127], v[42:43]
	v_pk_fma_f32 v[32:33], v[32:33], v[124:125], v[40:41]
	v_pk_fma_f32 v[40:41], v[30:31], v[122:123], v[46:47]
	v_pk_fma_f32 v[30:31], v[28:29], v[120:121], v[44:45]
	v_cvt_pk_bf16_f32 v28, v32, v33
	v_cvt_pk_bf16_f32 v29, v34, v35
	s_nop 0
	v_cvt_pk_bf16_f32 v30, v30, v31
	v_cvt_pk_bf16_f32 v31, v40, v41
	s_nop 0
	global_store_dwordx4 v[64:65], v[28:31], off offset:256
	s_nop 0
	s_nop 0
	v_lshlrev_b32_e32 v28, 16, v248
	v_and_b32_e32 v29, 0xffff0000, v248
	v_lshlrev_b32_e32 v30, 16, v249
	v_and_b32_e32 v31, 0xffff0000, v249
	v_lshlrev_b32_e32 v32, 16, v250
	v_and_b32_e32 v33, 0xffff0000, v250
	v_lshlrev_b32_e32 v34, 16, v251
	v_and_b32_e32 v35, 0xffff0000, v251
	v_pk_fma_f32 v[30:31], v[38:39], v[142:143], v[30:31]
	v_pk_fma_f32 v[28:29], v[36:37], v[140:141], v[28:29]
	v_pk_fma_f32 v[34:35], v[26:27], v[138:139], v[34:35]
	v_pk_fma_f32 v[26:27], v[24:25], v[136:137], v[32:33]
	v_cvt_pk_bf16_f32 v24, v28, v29
	v_cvt_pk_bf16_f32 v25, v30, v31
	v_lshl_add_u64 v[32:33], s[20:21], 0, v[160:161]
	v_cvt_pk_bf16_f32 v26, v26, v27
	v_cvt_pk_bf16_f32 v27, v34, v35
	v_lshl_add_u64 v[32:33], v[32:33], 0, v[176:177]
	global_store_dwordx4 v[48:49], v[24:27], off
	s_nop 0
	s_nop 0
	s_waitcnt vmcnt(14)
	v_lshlrev_b32_e32 v24, 16, v196
	v_and_b32_e32 v25, 0xffff0000, v196
	v_lshlrev_b32_e32 v26, 16, v197
	v_and_b32_e32 v27, 0xffff0000, v197
	v_lshlrev_b32_e32 v28, 16, v198
	v_and_b32_e32 v29, 0xffff0000, v198
	v_lshlrev_b32_e32 v30, 16, v199
	v_and_b32_e32 v31, 0xffff0000, v199
	v_pk_fma_f32 v[18:19], v[18:19], v[126:127], v[26:27]
	v_pk_fma_f32 v[16:17], v[16:17], v[124:125], v[24:25]
	v_pk_fma_f32 v[24:25], v[14:15], v[122:123], v[30:31]
	v_pk_fma_f32 v[14:15], v[12:13], v[120:121], v[28:29]
	v_cvt_pk_bf16_f32 v12, v16, v17
	v_cvt_pk_bf16_f32 v13, v18, v19
	s_nop 0
	v_cvt_pk_bf16_f32 v14, v14, v15
	v_cvt_pk_bf16_f32 v15, v24, v25
	s_nop 0
	global_store_dwordx4 v[48:49], v[12:15], off offset:256
	s_nop 0
	s_nop 0
	s_waitcnt vmcnt(13)
	v_lshlrev_b32_e32 v12, 16, v200
	v_and_b32_e32 v13, 0xffff0000, v200
	v_lshlrev_b32_e32 v14, 16, v201
	v_and_b32_e32 v15, 0xffff0000, v201
	v_lshlrev_b32_e32 v16, 16, v202
	v_and_b32_e32 v17, 0xffff0000, v202
	v_lshlrev_b32_e32 v18, 16, v203
	v_and_b32_e32 v19, 0xffff0000, v203
	v_pk_fma_f32 v[14:15], v[22:23], v[142:143], v[14:15]
	v_pk_fma_f32 v[12:13], v[20:21], v[140:141], v[12:13]
	v_pk_fma_f32 v[18:19], v[10:11], v[138:139], v[18:19]
	v_pk_fma_f32 v[10:11], v[8:9], v[136:137], v[16:17]
	v_cvt_pk_bf16_f32 v8, v12, v13
	v_cvt_pk_bf16_f32 v9, v14, v15
	s_nop 0
	v_cvt_pk_bf16_f32 v10, v10, v11
	v_cvt_pk_bf16_f32 v11, v18, v19
	s_nop 0
	global_store_dwordx4 v[32:33], v[8:11], off
	s_nop 0
	s_nop 0
	s_waitcnt vmcnt(12)
	v_lshlrev_b32_e32 v8, 16, v204
	v_and_b32_e32 v9, 0xffff0000, v204
	v_lshlrev_b32_e32 v10, 16, v205
	v_and_b32_e32 v11, 0xffff0000, v205
	v_lshlrev_b32_e32 v12, 16, v206
	v_and_b32_e32 v13, 0xffff0000, v206
	v_lshlrev_b32_e32 v14, 16, v207
	v_and_b32_e32 v15, 0xffff0000, v207
	v_pk_fma_f32 v[4:5], v[4:5], v[124:125], v[8:9]
	v_pk_fma_f32 v[8:9], v[2:3], v[122:123], v[14:15]
	v_pk_fma_f32 v[2:3], v[0:1], v[120:121], v[12:13]
	v_pk_fma_f32 v[6:7], v[6:7], v[126:127], v[10:11]
	v_cvt_pk_bf16_f32 v0, v4, v5
	s_nop 0
	v_cvt_pk_bf16_f32 v1, v6, v7
	v_cvt_pk_bf16_f32 v2, v2, v3
	v_cvt_pk_bf16_f32 v3, v8, v9
	global_store_dwordx4 v[32:33], v[0:3], off offset:256
	s_cbranch_vccnz .LBB0_1567
	s_andn2_b64 vcc, exec, s[4:5]
	s_cbranch_vccnz .LBB0_1566
	s_barrier
	s_branch .LBB0_1566

; __device__ __forceinline__ void st8(bf16_t* p, f32x4 a, f32x4 b) { u32x4 w; w.x = cvt_pk_bf16(a[0], a[1]); w.y = cvt_pk_bf16(a[2], a[3]); w.z = cvt_pk_bf16(b[0], b[1]); w.w = cvt_pk_bf16(b[2], b[3]); *(u32x4*)p = w; }
; __device__ __forceinline__ void ld8(const bf16_t* p, f32x4& a, f32x4& b) { const u32x4 r = *(const u32x4*)p;
;     a = (f32x4){__uint_as_float(r.x << 16), __uint_as_float(r.x & 0xffff0000u), __uint_as_float(r.y << 16), __uint_as_float(r.y & 0xffff0000u)};
;     b = (f32x4){__uint_as_float(r.z << 16), __uint_as_float(r.z & 0xffff0000u), __uint_as_float(r.w << 16), __uint_as_float(r.w & 0xffff0000u)}; }
;     __device__ __forceinline__ void operator()(const f32x4 (&acc)[2][2][4][2], const Unit& u, int wr, int wc, int fr, int fq) const {
;     ...
;             for (int n = 0; n < 2; ++n) gv[bj][n] = *(const f32x4*)(gp + col0 + bj * HALF + 4 * n);
; #pragma unroll
;         for (int ai = 0; ai < 2; ++ai)
; #pragma unroll
;             for (int m = 0; m < 4; ++m) { const size_t ro = (size_t)(wr * 64 + fr + ai * HALF + m * 16) * 1024 + col0;
; #pragma unroll
;                 for (int bj = 0; bj < 2; ++bj) {
;                     f32x4 r0, r1; ld8(rb + ro + bj * HALF, r0, r1);
;                     st8(ob + ro + bj * HALF, r0 + gv[bj][0] * acc[ai][bj][m][0], r1 + gv[bj][1] * acc[ai][bj][m][1]); } }
.LBB0_1789:
	v_lshl_or_b32 v176, s55, 8, v179
	v_ashrrev_i32_e32 v177, 31, v176
	v_lshl_add_u64 v[188:189], v[152:153], 0, v[176:177]
	v_lshl_add_u64 v[190:191], v[188:189], 1, s[16:17]
	global_load_dwordx4 v[184:187], v[190:191], off
	v_lshl_add_u64 v[132:133], v[176:177], 2, s[22:23]
	global_load_dwordx4 v[140:143], v[132:133], off
	global_load_dwordx4 v[136:139], v[132:133], off offset:16
	s_lshl_b64 s[18:19], s[18:19], 2
	s_add_u32 s18, s28, s18
	s_addc_u32 s19, s27, s19
	v_lshl_add_u64 v[188:189], v[188:189], 2, s[18:19]
	global_load_dwordx4 v[128:131], v[132:133], off offset:528
	s_nop 0
	global_load_dwordx4 v[132:135], v[132:133], off offset:512
	s_and_b64 vcc, exec, s[0:1]
	s_mov_b64 s[0:1], -1
	global_load_dwordx4 v[198:201], v[190:191], off offset:256
	v_lshl_add_u64 v[196:197], v[154:155], 0, v[176:177]
	v_lshl_add_u64 v[196:197], v[196:197], 1, s[16:17]
	global_load_dwordx4 v[202:205], v[196:197], off
	v_lshl_add_u64 v[196:197], v[154:155], 0, v[176:177]
	v_lshl_add_u64 v[196:197], v[196:197], 1, s[16:17]
	global_load_dwordx4 v[206:209], v[196:197], off offset:256
	v_lshl_add_u64 v[196:197], v[156:157], 0, v[176:177]
	v_lshl_add_u64 v[196:197], v[196:197], 1, s[16:17]
	global_load_dwordx4 v[210:213], v[196:197], off
	v_lshl_add_u64 v[196:197], v[156:157], 0, v[176:177]
	v_lshl_add_u64 v[196:197], v[196:197], 1, s[16:17]
	global_load_dwordx4 v[214:217], v[196:197], off offset:256
	v_lshl_add_u64 v[196:197], v[158:159], 0, v[176:177]
	v_lshl_add_u64 v[196:197], v[196:197], 1, s[16:17]
	global_load_dwordx4 v[218:221], v[196:197], off
	v_lshl_add_u64 v[196:197], v[158:159], 0, v[176:177]
	v_lshl_add_u64 v[196:197], v[196:197], 1, s[16:17]
	global_load_dwordx4 v[222:225], v[196:197], off offset:256
	v_lshl_add_u64 v[196:197], v[160:161], 0, v[176:177]
	v_lshl_add_u64 v[196:197], v[196:197], 1, s[16:17]
	global_load_dwordx4 v[226:229], v[196:197], off
	v_lshl_add_u64 v[196:197], v[160:161], 0, v[176:177]
	v_lshl_add_u64 v[196:197], v[196:197], 1, s[16:17]
	global_load_dwordx4 v[240:243], v[196:197], off offset:256
	v_lshl_add_u64 v[196:197], v[162:163], 0, v[176:177]
	v_lshl_add_u64 v[196:197], v[196:197], 1, s[16:17]
	global_load_dwordx4 v[244:247], v[196:197], off
	v_lshl_add_u64 v[196:197], v[162:163], 0, v[176:177]
	v_lshl_add_u64 v[196:197], v[196:197], 1, s[16:17]
	global_load_dwordx4 v[248:251], v[196:197], off offset:256
	s_waitcnt vmcnt(0)
	v_lshlrev_b32_e32 v192, 16, v184
	v_and_b32_e32 v193, 0xffff0000, v184
	v_lshlrev_b32_e32 v184, 16, v185
	v_and_b32_e32 v185, 0xffff0000, v185
	v_lshlrev_b32_e32 v194, 16, v186
	v_and_b32_e32 v195, 0xffff0000, v186
	v_lshlrev_b32_e32 v186, 16, v187
	v_and_b32_e32 v187, 0xffff0000, v187
	v_pk_fma_f32 v[126:127], v[126:127], v[142:143], v[184:185]
	v_pk_fma_f32 v[124:125], v[124:125], v[140:141], v[192:193]
	v_pk_fma_f32 v[122:123], v[122:123], v[138:139], v[186:187]
	v_pk_fma_f32 v[120:121], v[120:121], v[136:137], v[194:195]
	global_store_dwordx4 v[188:189], v[124:127], off
	global_store_dwordx4 v[188:189], v[120:123], off offset:16
	v_lshl_add_u64 v[124:125], v[154:155], 0, v[176:177]
	v_lshl_add_u64 v[126:127], v[124:125], 1, s[16:17]
	s_nop 0
	v_lshlrev_b32_e32 v184, 16, v198
	v_and_b32_e32 v185, 0xffff0000, v198
	v_lshlrev_b32_e32 v120, 16, v199
	v_and_b32_e32 v121, 0xffff0000, v199
	v_lshlrev_b32_e32 v186, 16, v200
	v_and_b32_e32 v187, 0xffff0000, v200
	v_lshlrev_b32_e32 v122, 16, v201
	v_and_b32_e32 v123, 0xffff0000, v201
	v_lshl_add_u64 v[196:197], v[164:165], 0, v[176:177]
	v_lshl_add_u64 v[196:197], v[196:197], 1, s[16:17]
	global_load_dwordx4 v[198:201], v[196:197], off
	v_pk_fma_f32 v[114:115], v[114:115], v[134:135], v[120:121]
	v_pk_fma_f32 v[112:113], v[112:113], v[132:133], v[184:185]
	v_pk_fma_f32 v[110:111], v[110:111], v[130:131], v[122:123]
	v_pk_fma_f32 v[108:109], v[108:109], v[128:129], v[186:187]
	global_store_dwordx4 v[188:189], v[112:115], off offset:512
	global_store_dwordx4 v[188:189], v[108:111], off offset:528
	v_lshl_add_u64 v[112:113], v[124:125], 2, s[18:19]
	s_nop 0
	v_lshlrev_b32_e32 v114, 16, v202
	v_and_b32_e32 v115, 0xffff0000, v202
	v_lshlrev_b32_e32 v108, 16, v203
	v_and_b32_e32 v109, 0xffff0000, v203
	v_lshlrev_b32_e32 v120, 16, v204
	v_and_b32_e32 v121, 0xffff0000, v204
	v_lshlrev_b32_e32 v122, 16, v205
	v_and_b32_e32 v123, 0xffff0000, v205
	v_lshl_add_u64 v[196:197], v[164:165], 0, v[176:177]
	v_lshl_add_u64 v[196:197], v[196:197], 1, s[16:17]
	global_load_dwordx4 v[202:205], v[196:197], off offset:256
	v_pk_fma_f32 v[110:111], v[118:119], v[142:143], v[108:109]
	v_pk_fma_f32 v[108:109], v[116:117], v[140:141], v[114:115]
	v_pk_fma_f32 v[106:107], v[106:107], v[138:139], v[122:123]
	v_pk_fma_f32 v[104:105], v[104:105], v[136:137], v[120:121]
	global_store_dwordx4 v[112:113], v[108:111], off
	global_store_dwordx4 v[112:113], v[104:107], off offset:16
	v_lshl_add_u64 v[108:109], v[156:157], 0, v[176:177]
	v_lshl_add_u64 v[110:111], v[108:109], 1, s[16:17]
	s_nop 0
	v_lshlrev_b32_e32 v114, 16, v206
	v_and_b32_e32 v115, 0xffff0000, v206
	v_lshlrev_b32_e32 v104, 16, v207
	v_and_b32_e32 v105, 0xffff0000, v207
	v_lshlrev_b32_e32 v116, 16, v208
	v_and_b32_e32 v117, 0xffff0000, v208
	v_lshlrev_b32_e32 v106, 16, v209
	v_and_b32_e32 v107, 0xffff0000, v209
	v_lshl_add_u64 v[196:197], v[166:167], 0, v[176:177]
	v_lshl_add_u64 v[196:197], v[196:197], 1, s[16:17]
	global_load_dwordx4 v[206:209], v[196:197], off
	v_pk_fma_f32 v[98:99], v[98:99], v[134:135], v[104:105]
	v_pk_fma_f32 v[96:97], v[96:97], v[132:133], v[114:115]
	v_pk_fma_f32 v[94:95], v[94:95], v[130:131], v[106:107]
	v_pk_fma_f32 v[92:93], v[92:93], v[128:129], v[116:117]
; __device__ __forceinline__ void st8(bf16_t* p, f32x4 a, f32x4 b) { u32x4 w; w.x = cvt_pk_bf16(a[0], a[1]); w.y = cvt_pk_bf16(a[2], a[3]); w.z = cvt_pk_bf16(b[0], b[1]); w.w = cvt_pk_bf16(b[2], b[3]); *(u32x4*)p = w; }
; __device__ __forceinline__ void ld8(const bf16_t* p, f32x4& a, f32x4& b) { const u32x4 r = *(const u32x4*)p;
;     a = (f32x4){__uint_as_float(r.x << 16), __uint_as_float(r.x & 0xffff0000u), __uint_as_float(r.y << 16), __uint_as_float(r.y & 0xffff0000u)};
;     b = (f32x4){__uint_as_float(r.z << 16), __uint_as_float(r.z & 0xffff0000u), __uint_as_float(r.w << 16), __uint_as_float(r.w & 0xffff0000u)}; }
;     __device__ __forceinline__ void operator()(const f32x4 (&acc)[2][2][4][2], const Unit& u, int wr, int wc, int fr, int fq) const {
;     ...
;             for (int n = 0; n < 2; ++n) gv[bj][n] = *(const f32x4*)(gp + col0 + bj * HALF + 4 * n);
; #pragma unroll
;         for (int ai = 0; ai < 2; ++ai)
; #pragma unroll
;             for (int m = 0; m < 4; ++m) { const size_t ro = (size_t)(wr * 64 + fr + ai * HALF + m * 16) * 1024 + col0;
; #pragma unroll
;                 for (int bj = 0; bj < 2; ++bj) {
;                     f32x4 r0, r1; ld8(rb + ro + bj * HALF, r0, r1);
;                     st8(ob + ro + bj * HALF, r0 + gv[bj][0] * acc[ai][bj][m][0], r1 + gv[bj][1] * acc[ai][bj][m][1]); } }
	global_store_dwordx4 v[112:113], v[96:99], off offset:512
	global_store_dwordx4 v[112:113], v[92:95], off offset:528
	v_lshl_add_u64 v[96:97], v[108:109], 2, s[18:19]
	s_nop 0
	v_lshlrev_b32_e32 v98, 16, v210
	v_and_b32_e32 v99, 0xffff0000, v210
	v_lshlrev_b32_e32 v92, 16, v211
	v_and_b32_e32 v93, 0xffff0000, v211
	v_lshlrev_b32_e32 v104, 16, v212
	v_and_b32_e32 v105, 0xffff0000, v212
	v_lshlrev_b32_e32 v106, 16, v213
	v_and_b32_e32 v107, 0xffff0000, v213
	v_lshl_add_u64 v[196:197], v[166:167], 0, v[176:177]
	v_lshl_add_u64 v[196:197], v[196:197], 1, s[16:17]
	global_load_dwordx4 v[210:213], v[196:197], off offset:256
	v_pk_fma_f32 v[94:95], v[102:103], v[142:143], v[92:93]
	v_pk_fma_f32 v[92:93], v[100:101], v[140:141], v[98:99]
	v_pk_fma_f32 v[90:91], v[90:91], v[138:139], v[106:107]
	v_pk_fma_f32 v[88:89], v[88:89], v[136:137], v[104:105]
	global_store_dwordx4 v[96:97], v[92:95], off
	global_store_dwordx4 v[96:97], v[88:91], off offset:16
	v_lshl_add_u64 v[92:93], v[158:159], 0, v[176:177]
	v_lshl_add_u64 v[94:95], v[92:93], 1, s[16:17]
	s_nop 0
	v_lshlrev_b32_e32 v98, 16, v214
	v_and_b32_e32 v99, 0xffff0000, v214
	v_lshlrev_b32_e32 v88, 16, v215
	v_and_b32_e32 v89, 0xffff0000, v215
	v_lshlrev_b32_e32 v100, 16, v216
	v_and_b32_e32 v101, 0xffff0000, v216
	v_lshlrev_b32_e32 v90, 16, v217
	v_and_b32_e32 v91, 0xffff0000, v217
	v_pk_fma_f32 v[82:83], v[82:83], v[134:135], v[88:89]
	v_pk_fma_f32 v[80:81], v[80:81], v[132:133], v[98:99]
	v_pk_fma_f32 v[78:79], v[78:79], v[130:131], v[90:91]
	v_pk_fma_f32 v[76:77], v[76:77], v[128:129], v[100:101]
	global_store_dwordx4 v[96:97], v[80:83], off offset:512
	global_store_dwordx4 v[96:97], v[76:79], off offset:528
	v_lshl_add_u64 v[80:81], v[92:93], 2, s[18:19]
	s_nop 0
	v_lshlrev_b32_e32 v82, 16, v218
	v_and_b32_e32 v83, 0xffff0000, v218
	v_lshlrev_b32_e32 v76, 16, v219
	v_and_b32_e32 v77, 0xffff0000, v219
	v_lshlrev_b32_e32 v88, 16, v220
	v_and_b32_e32 v89, 0xffff0000, v220
	v_lshlrev_b32_e32 v90, 16, v221
	v_and_b32_e32 v91, 0xffff0000, v221
	v_pk_fma_f32 v[78:79], v[86:87], v[142:143], v[76:77]
	v_pk_fma_f32 v[76:77], v[84:85], v[140:141], v[82:83]
	v_pk_fma_f32 v[74:75], v[74:75], v[138:139], v[90:91]
	v_pk_fma_f32 v[72:73], v[72:73], v[136:137], v[88:89]
	global_store_dwordx4 v[80:81], v[76:79], off
	global_store_dwordx4 v[80:81], v[72:75], off offset:16
	v_lshl_add_u64 v[76:77], v[160:161], 0, v[176:177]
	v_lshl_add_u64 v[78:79], v[76:77], 1, s[16:17]
	s_nop 0
	v_lshlrev_b32_e32 v82, 16, v222
	v_and_b32_e32 v83, 0xffff0000, v222
	v_lshlrev_b32_e32 v72, 16, v223
	v_and_b32_e32 v73, 0xffff0000, v223
	v_lshlrev_b32_e32 v84, 16, v224
	v_and_b32_e32 v85, 0xffff0000, v224
	v_lshlrev_b32_e32 v74, 16, v225
	v_and_b32_e32 v75, 0xffff0000, v225
	v_pk_fma_f32 v[70:71], v[70:71], v[134:135], v[72:73]
	v_pk_fma_f32 v[68:69], v[68:69], v[132:133], v[82:83]
	v_pk_fma_f32 v[66:67], v[66:67], v[130:131], v[74:75]
	v_pk_fma_f32 v[64:65], v[64:65], v[128:129], v[84:85]
	global_store_dwordx4 v[80:81], v[68:71], off offset:512
	global_store_dwordx4 v[80:81], v[64:67], off offset:528
	v_lshl_add_u64 v[68:69], v[76:77], 2, s[18:19]
	s_nop 0
	v_lshlrev_b32_e32 v70, 16, v226
	v_and_b32_e32 v71, 0xffff0000, v226
	v_lshlrev_b32_e32 v64, 16, v227
	v_and_b32_e32 v65, 0xffff0000, v227
	v_lshlrev_b32_e32 v72, 16, v228
	v_and_b32_e32 v73, 0xffff0000, v228
	v_lshlrev_b32_e32 v66, 16, v229
	v_and_b32_e32 v67, 0xffff0000, v229
	v_pk_fma_f32 v[62:63], v[62:63], v[142:143], v[64:65]
	v_pk_fma_f32 v[60:61], v[60:61], v[140:141], v[70:71]
	v_pk_fma_f32 v[58:59], v[58:59], v[138:139], v[66:67]
	v_pk_fma_f32 v[56:57], v[56:57], v[136:137], v[72:73]
	global_store_dwordx4 v[68:69], v[60:63], off
	global_store_dwordx4 v[68:69], v[56:59], off offset:16
	v_lshl_add_u64 v[60:61], v[162:163], 0, v[176:177]
	v_lshl_add_u64 v[62:63], v[60:61], 1, s[16:17]
	s_nop 0
	v_lshlrev_b32_e32 v64, 16, v240
	v_and_b32_e32 v65, 0xffff0000, v240
	v_lshlrev_b32_e32 v56, 16, v241
	v_and_b32_e32 v57, 0xffff0000, v241
	v_lshlrev_b32_e32 v66, 16, v242
	v_and_b32_e32 v67, 0xffff0000, v242
	v_lshlrev_b32_e32 v58, 16, v243
	v_and_b32_e32 v59, 0xffff0000, v243
	v_pk_fma_f32 v[50:51], v[50:51], v[134:135], v[56:57]
	v_pk_fma_f32 v[48:49], v[48:49], v[132:133], v[64:65]
	v_pk_fma_f32 v[46:47], v[46:47], v[130:131], v[58:59]
	v_pk_fma_f32 v[44:45], v[44:45], v[128:129], v[66:67]
	global_store_dwordx4 v[68:69], v[48:51], off offset:512
	global_store_dwordx4 v[68:69], v[44:47], off offset:528
	v_lshl_add_u64 v[48:49], v[60:61], 2, s[18:19]
	s_nop 0
	v_lshlrev_b32_e32 v50, 16, v244
	v_and_b32_e32 v51, 0xffff0000, v244
	v_lshlrev_b32_e32 v44, 16, v245
	v_and_b32_e32 v45, 0xffff0000, v245
	v_lshlrev_b32_e32 v56, 16, v246
	v_and_b32_e32 v57, 0xffff0000, v246
	v_lshlrev_b32_e32 v58, 16, v247
	v_and_b32_e32 v59, 0xffff0000, v247
	v_pk_fma_f32 v[46:47], v[54:55], v[142:143], v[44:45]
	v_pk_fma_f32 v[44:45], v[52:53], v[140:141], v[50:51]
	v_pk_fma_f32 v[42:43], v[42:43], v[138:139], v[58:59]
	v_pk_fma_f32 v[40:41], v[40:41], v[136:137], v[56:57]
	global_store_dwordx4 v[48:49], v[44:47], off
	global_store_dwordx4 v[48:49], v[40:43], off offset:16
	v_lshl_add_u64 v[44:45], v[164:165], 0, v[176:177]
	v_lshl_add_u64 v[46:47], v[44:45], 1, s[16:17]
	s_nop 0
	v_lshlrev_b32_e32 v50, 16, v248
	v_and_b32_e32 v51, 0xffff0000, v248
	v_lshlrev_b32_e32 v40, 16, v249
	v_and_b32_e32 v41, 0xffff0000, v249
	v_lshlrev_b32_e32 v52, 16, v250
	v_and_b32_e32 v53, 0xffff0000, v250
	v_lshlrev_b32_e32 v42, 16, v251
	v_and_b32_e32 v43, 0xffff0000, v251
	v_pk_fma_f32 v[34:35], v[34:35], v[134:135], v[40:41]
	v_pk_fma_f32 v[32:33], v[32:33], v[132:133], v[50:51]
	v_pk_fma_f32 v[30:31], v[30:31], v[130:131], v[42:43]
	v_pk_fma_f32 v[28:29], v[28:29], v[128:129], v[52:53]
	global_store_dwordx4 v[48:49], v[32:35], off offset:512
	global_store_dwordx4 v[48:49], v[28:31], off offset:528
	v_lshl_add_u64 v[32:33], v[44:45], 2, s[18:19]
	s_nop 0
	s_waitcnt vmcnt(25)
; __device__ __forceinline__ void st8(bf16_t* p, f32x4 a, f32x4 b) { u32x4 w; w.x = cvt_pk_bf16(a[0], a[1]); w.y = cvt_pk_bf16(a[2], a[3]); w.z = cvt_pk_bf16(b[0], b[1]); w.w = cvt_pk_bf16(b[2], b[3]); *(u32x4*)p = w; }
; __device__ __forceinline__ void ld8(const bf16_t* p, f32x4& a, f32x4& b) { const u32x4 r = *(const u32x4*)p;
;     a = (f32x4){__uint_as_float(r.x << 16), __uint_as_float(r.x & 0xffff0000u), __uint_as_float(r.y << 16), __uint_as_float(r.y & 0xffff0000u)};
;     b = (f32x4){__uint_as_float(r.z << 16), __uint_as_float(r.z & 0xffff0000u), __uint_as_float(r.w << 16), __uint_as_float(r.w & 0xffff0000u)}; }
;     __device__ __forceinline__ void operator()(const f32x4 (&acc)[2][2][4][2], const Unit& u, int wr, int wc, int fr, int fq) const {
;     ...
;             for (int n = 0; n < 2; ++n) gv[bj][n] = *(const f32x4*)(gp + col0 + bj * HALF + 4 * n);
; #pragma unroll
;         for (int ai = 0; ai < 2; ++ai)
; #pragma unroll
;             for (int m = 0; m < 4; ++m) { const size_t ro = (size_t)(wr * 64 + fr + ai * HALF + m * 16) * 1024 + col0;
; #pragma unroll
;                 for (int bj = 0; bj < 2; ++bj) {
;                     f32x4 r0, r1; ld8(rb + ro + bj * HALF, r0, r1);
;                     st8(ob + ro + bj * HALF, r0 + gv[bj][0] * acc[ai][bj][m][0], r1 + gv[bj][1] * acc[ai][bj][m][1]); } }
	v_lshlrev_b32_e32 v34, 16, v198
	v_and_b32_e32 v35, 0xffff0000, v198
	v_lshlrev_b32_e32 v28, 16, v199
	v_and_b32_e32 v29, 0xffff0000, v199
	v_lshlrev_b32_e32 v40, 16, v200
	v_and_b32_e32 v41, 0xffff0000, v200
	v_lshlrev_b32_e32 v42, 16, v201
	v_and_b32_e32 v43, 0xffff0000, v201
	v_pk_fma_f32 v[30:31], v[38:39], v[142:143], v[28:29]
	v_pk_fma_f32 v[28:29], v[36:37], v[140:141], v[34:35]
	v_pk_fma_f32 v[26:27], v[26:27], v[138:139], v[42:43]
	v_pk_fma_f32 v[24:25], v[24:25], v[136:137], v[40:41]
	global_store_dwordx4 v[32:33], v[28:31], off
	global_store_dwordx4 v[32:33], v[24:27], off offset:16
	v_lshl_add_u64 v[28:29], v[166:167], 0, v[176:177]
	v_lshl_add_u64 v[30:31], v[28:29], 1, s[16:17]
	s_nop 0
	s_waitcnt vmcnt(24)
	v_lshlrev_b32_e32 v34, 16, v202
	v_and_b32_e32 v35, 0xffff0000, v202
	v_lshlrev_b32_e32 v24, 16, v203
	v_and_b32_e32 v25, 0xffff0000, v203
	v_lshlrev_b32_e32 v36, 16, v204
	v_and_b32_e32 v37, 0xffff0000, v204
	v_lshlrev_b32_e32 v26, 16, v205
	v_and_b32_e32 v27, 0xffff0000, v205
	v_pk_fma_f32 v[18:19], v[18:19], v[134:135], v[24:25]
	v_pk_fma_f32 v[16:17], v[16:17], v[132:133], v[34:35]
	v_pk_fma_f32 v[14:15], v[14:15], v[130:131], v[26:27]
	v_pk_fma_f32 v[12:13], v[12:13], v[128:129], v[36:37]
	global_store_dwordx4 v[32:33], v[16:19], off offset:512
	global_store_dwordx4 v[32:33], v[12:15], off offset:528
	v_lshl_add_u64 v[16:17], v[28:29], 2, s[18:19]
	s_nop 0
	s_waitcnt vmcnt(23)
	v_lshlrev_b32_e32 v18, 16, v206
	v_and_b32_e32 v19, 0xffff0000, v206
	v_lshlrev_b32_e32 v12, 16, v207
	v_and_b32_e32 v13, 0xffff0000, v207
	v_lshlrev_b32_e32 v24, 16, v208
	v_and_b32_e32 v25, 0xffff0000, v208
	v_lshlrev_b32_e32 v26, 16, v209
	v_and_b32_e32 v27, 0xffff0000, v209
	v_pk_fma_f32 v[14:15], v[22:23], v[142:143], v[12:13]
	v_pk_fma_f32 v[12:13], v[20:21], v[140:141], v[18:19]
	v_pk_fma_f32 v[10:11], v[10:11], v[138:139], v[26:27]
	v_pk_fma_f32 v[8:9], v[8:9], v[136:137], v[24:25]
	global_store_dwordx4 v[16:17], v[12:15], off
	global_store_dwordx4 v[16:17], v[8:11], off offset:16
	s_nop 0
	s_waitcnt vmcnt(22)
	v_lshlrev_b32_e32 v12, 16, v210
	v_and_b32_e32 v13, 0xffff0000, v210
	v_lshlrev_b32_e32 v8, 16, v211
	v_and_b32_e32 v9, 0xffff0000, v211
	v_lshlrev_b32_e32 v14, 16, v212
	v_and_b32_e32 v15, 0xffff0000, v212
	v_lshlrev_b32_e32 v10, 16, v213
	v_and_b32_e32 v11, 0xffff0000, v213
	v_pk_fma_f32 v[6:7], v[6:7], v[134:135], v[8:9]
	v_pk_fma_f32 v[4:5], v[4:5], v[132:133], v[12:13]
	v_pk_fma_f32 v[2:3], v[2:3], v[130:131], v[10:11]
	v_pk_fma_f32 v[0:1], v[0:1], v[128:129], v[14:15]
	global_store_dwordx4 v[16:17], v[4:7], off offset:512
	global_store_dwordx4 v[16:17], v[0:3], off offset:528
	s_cbranch_vccnz .LBB0_1771
	s_andn2_b64 vcc, exec, s[6:7]
	s_cbranch_vccnz .LBB0_1770
	s_barrier
	s_branch .LBB0_1770
